# peer_query sub-key scores: the 16 loop-invariant SK fragment loads of the first key half issued before the accumulator staging (into free registers) instead of 2 steps ahead inside the MFMA chain; VGP
# speedup vs baseline: 1.0066x; 1.0008x over previous
; DI int otid() { int t = __builtin_amdgcn_workitem_id_x(); asm volatile("" : "+v"(t)); return t; }
; DI unsigned pack2(float a, float b) { const f32x2 v = {a, b}; return __builtin_bit_cast(unsigned, __builtin_convertvector(v, bf16v2)); }
; template <int SWAP>
; DI void stage8(const f32x4 (&acc)[2][2][4][2], u16* Ct) {
;   const int tid = otid(), wid = tid >> 6, lane = tid & 63, wr = wid >> 2, wc = wid & 3, fr = lane & 15, fq = lane >> 4;
; #pragma unroll
;   for (int ai = 0; ai < 2; ++ai)
; #pragma unroll
;     for (int bj = 0; bj < 2; ++bj)
; #pragma unroll
;       for (int m = 0; m < 4; ++m)
; #pragma unroll
;         for (int n = 0; n < 2; ++n) {
;           uint2 o; o.x = pack2(acc[ai][bj][m][n][0], acc[ai][bj][m][n][1]); o.y = pack2(acc[ai][bj][m][n][2], acc[ai][bj][m][n][3]);
;           if (SWAP) *(uint2*)(Ct + (ai * 128 + wr * 64 + m * 16 + fr) * CT_LD + bj * 128 + wc * 32 + n * 16 + fq * 4) = o;
;           else *(uint2*)(Ct + (bj * 128 + wc * 32 + n * 16 + fr) * CT_LD + ai * 128 + wr * 64 + m * 16 + fq * 4) = o;
;         }
; }
; DI void phase_peer_query(const Params& p, char* lds) {
;     ...
;         const bf16x8 a0 = ldfrag(Ct + (wm * 64 + l31) * CT_LD + pp * 128 + kk * 16 + 8 * hh), a1 = ldfrag(Ct + (wm * 64 + 32 + l31) * CT_LD + pp * 128 + kk * 16 + 8 * hh);
;         const bf16x8 b0 = ldfrag(SK + (size_t)(pp * 128 + wn * 64 + l31) * 128 + kk * 16 + 8 * hh), b1 = ldfrag(SK + (size_t)(pp * 128 + wn * 64 + 32 + l31) * 128 + kk * 16 + 8 * hh);
.LBB0_1124:
	s_or_b64 exec, exec, s[16:17]
	v_mov_b32_e32 v128, v222
	s_waitcnt vmcnt(0)
	s_barrier
	global_load_dwordx4 v[132:135], v[224:225], off
	global_load_dwordx4 v[142:145], v[226:227], off
	global_load_dwordx4 v[146:149], v[224:225], off offset:32
	global_load_dwordx4 v[150:153], v[226:227], off offset:32
	global_load_dwordx4 v[158:161], v[224:225], off offset:64
	global_load_dwordx4 v[162:165], v[226:227], off offset:64
	global_load_dwordx4 v[166:169], v[224:225], off offset:96
	global_load_dwordx4 v[170:173], v[226:227], off offset:96
	global_load_dwordx4 v[174:177], v[224:225], off offset:128
	global_load_dwordx4 v[182:185], v[226:227], off offset:128
	global_load_dwordx4 v[186:189], v[224:225], off offset:160
	global_load_dwordx4 v[138:141], v[226:227], off offset:160
	global_load_dwordx4 v[238:241], v[224:225], off offset:192
	global_load_dwordx4 v[242:245], v[226:227], off offset:192
	global_load_dwordx4 v[246:249], v[224:225], off offset:224
	global_load_dwordx4 v[252:255], v[226:227], off offset:224
	v_cvt_pk_bf16_f32 v92, v92, v93
	v_and_b32_e32 v129, 15, v128
	v_lshrrev_b32_e32 v130, 2, v128
	v_and_or_b32 v129, v130, s43, v129
	v_lshrrev_b32_e32 v130, 1, v128
	v_and_b32_e32 v128, 0xc0, v128
	v_and_b32_e32 v130, 24, v130
	v_add3_u32 v128, 0, v128, v130
	v_mul_lo_u32 v129, v129, s42
	v_add_u32_e32 v130, v128, v129
	v_cvt_pk_bf16_f32 v93, v94, v95
	v_add_u32_e32 v94, 0x6000, v130
	v_cvt_pk_bf16_f32 v60, v60, v61
	v_cvt_pk_bf16_f32 v61, v62, v63
	v_cvt_pk_bf16_f32 v52, v52, v53
	v_cvt_pk_bf16_f32 v53, v54, v55
	ds_write2_b64 v94, v[60:61], v[52:53] offset0:128 offset1:132
	v_add_u32_e32 v60, 0x10800, v129
	v_add_u32_e32 v61, v128, v60
	v_cvt_pk_bf16_f32 v52, v76, v77
	v_cvt_pk_bf16_f32 v53, v78, v79
	v_cvt_pk_bf16_f32 v54, v68, v69
	v_cvt_pk_bf16_f32 v55, v70, v71
	ds_write2_b64 v61, v[52:53], v[54:55] offset1:4
	v_add_u32_e32 v54, 0x12900, v129
	v_add_u32_e32 v55, v128, v54
	v_cvt_pk_bf16_f32 v52, v56, v57
	v_cvt_pk_bf16_f32 v53, v58, v59
	v_cvt_pk_bf16_f32 v48, v48, v49
	v_cvt_pk_bf16_f32 v49, v50, v51
	ds_write2_b64 v55, v[52:53], v[48:49] offset1:4
	v_add_u32_e32 v48, 0x14a00, v129
	v_add_u32_e32 v49, v128, v48
	v_cvt_pk_bf16_f32 v44, v44, v45
	v_cvt_pk_bf16_f32 v45, v46, v47
	v_cvt_pk_bf16_f32 v40, v40, v41
	v_cvt_pk_bf16_f32 v41, v42, v43
	v_cvt_pk_bf16_f32 v84, v84, v85
	v_cvt_pk_bf16_f32 v85, v86, v87
	ds_write2_b64 v49, v[44:45], v[40:41] offset1:4
	v_add_u32_e32 v40, 0x16b00, v129
	ds_write2_b64 v94, v[92:93], v[84:85] offset0:96 offset1:100
	v_add_u32_e32 v92, 0x100, v128
	v_add_u32_e32 v41, v128, v40
	v_cvt_pk_bf16_f32 v36, v36, v37
	v_cvt_pk_bf16_f32 v37, v38, v39
	v_cvt_pk_bf16_f32 v32, v32, v33
	v_cvt_pk_bf16_f32 v33, v34, v35
	ds_write2_b64 v41, v[36:37], v[32:33] offset1:4
	v_add_u32_e32 v32, v92, v60
	v_cvt_pk_bf16_f32 v28, v28, v29
	v_cvt_pk_bf16_f32 v29, v30, v31
	v_cvt_pk_bf16_f32 v24, v24, v25
	v_cvt_pk_bf16_f32 v25, v26, v27
	ds_write2_b64 v32, v[28:29], v[24:25] offset1:4
	v_add_u32_e32 v24, v92, v54
	v_cvt_pk_bf16_f32 v20, v20, v21
	v_cvt_pk_bf16_f32 v21, v22, v23
	v_cvt_pk_bf16_f32 v16, v16, v17
	v_cvt_pk_bf16_f32 v17, v18, v19
	v_cvt_pk_bf16_f32 v84, v100, v101
	v_cvt_pk_bf16_f32 v85, v102, v103
	v_cvt_pk_bf16_f32 v86, v96, v97
	v_cvt_pk_bf16_f32 v87, v98, v99
	ds_write2_b64 v24, v[20:21], v[16:17] offset1:4
	v_add_u32_e32 v16, v92, v48
	v_cvt_pk_bf16_f32 v12, v12, v13
	v_cvt_pk_bf16_f32 v13, v14, v15
	v_cvt_pk_bf16_f32 v8, v8, v9
	v_cvt_pk_bf16_f32 v9, v10, v11
	v_cvt_pk_bf16_f32 v124, v124, v125
	v_cvt_pk_bf16_f32 v125, v126, v127
	v_cvt_pk_bf16_f32 v120, v120, v121
	v_cvt_pk_bf16_f32 v121, v122, v123
	v_cvt_pk_bf16_f32 v116, v116, v117
	v_cvt_pk_bf16_f32 v117, v118, v119
	v_cvt_pk_bf16_f32 v112, v112, v113
	v_cvt_pk_bf16_f32 v113, v114, v115
	v_add_u32_e32 v114, 0x2000, v130
	v_cvt_pk_bf16_f32 v108, v108, v109
	v_cvt_pk_bf16_f32 v109, v110, v111
	v_cvt_pk_bf16_f32 v104, v104, v105
	v_cvt_pk_bf16_f32 v105, v106, v107
	v_add_u32_e32 v106, 0x4000, v130
	ds_write2_b64 v130, v[84:85], v[86:87] offset0:32 offset1:36
	v_cvt_pk_bf16_f32 v84, v88, v89
	v_cvt_pk_bf16_f32 v85, v90, v91
	v_cvt_pk_bf16_f32 v80, v80, v81
	v_cvt_pk_bf16_f32 v81, v82, v83
	v_cvt_pk_bf16_f32 v72, v72, v73
	v_cvt_pk_bf16_f32 v73, v74, v75
	v_cvt_pk_bf16_f32 v64, v64, v65
	v_cvt_pk_bf16_f32 v65, v66, v67
	ds_write2_b64 v16, v[12:13], v[8:9] offset1:4
	v_add_u32_e32 v8, v92, v40
	v_cvt_pk_bf16_f32 v4, v4, v5
	v_cvt_pk_bf16_f32 v5, v6, v7
	v_cvt_pk_bf16_f32 v0, v0, v1
	v_cvt_pk_bf16_f32 v1, v2, v3
	ds_write2_b64 v130, v[124:125], v[120:121] offset1:4
	ds_write2_b64 v114, v[116:117], v[112:113] offset0:32 offset1:36
	ds_write2_b64 v106, v[108:109], v[104:105] offset0:64 offset1:68
	ds_write2_b64 v114, v[84:85], v[80:81] offset0:64 offset1:68
	ds_write2_b64 v106, v[72:73], v[64:65] offset0:96 offset1:100
	ds_write2_b64 v8, v[4:5], v[0:1] offset1:4
	s_waitcnt lgkmcnt(0)
	s_barrier
; #define MFMA(a, b, c) __builtin_amdgcn_mfma_f32_32x32x16_bf16((a), (b), (c), 0, 0, 0)
; DI f32x16 zero16() { f32x16 z; for (int i = 0; i < 16; ++i) z[i] = 0.f; return z; }
; DI void phase_peer_query(const Params& p, char* lds) {
;     ...
;     f32x16 sacc[2][2][2];
; #pragma unroll
;     for (int pp = 0; pp < 2; ++pp) {
; #pragma unroll
;       for (int i = 0; i < 2; ++i) for (int j = 0; j < 2; ++j) sacc[pp][i][j] = zero16();
; #pragma unroll
;       for (int kk = 0; kk < 8; ++kk) {
;         const bf16x8 a0 = ldfrag(Ct + (wm * 64 + l31) * CT_LD + pp * 128 + kk * 16 + 8 * hh), a1 = ldfrag(Ct + (wm * 64 + 32 + l31) * CT_LD + pp * 128 + kk * 16 + 8 * hh);
;         const bf16x8 b0 = ldfrag(SK + (size_t)(pp * 128 + wn * 64 + l31) * 128 + kk * 16 + 8 * hh), b1 = ldfrag(SK + (size_t)(pp * 128 + wn * 64 + 32 + l31) * 128 + kk * 16 + 8 * hh);
;         sacc[pp][0][0] = MFMA(a0, b0, sacc[pp][0][0]); sacc[pp][0][1] = MFMA(a0, b1, sacc[pp][0][1]);
;         sacc[pp][1][0] = MFMA(a1, b0, sacc[pp][1][0]); sacc[pp][1][1] = MFMA(a1, b1, sacc[pp][1][1]);
;       }
;     }
	s_waitcnt vmcnt(0)
	ds_read_b128 v[4:7], v233
	ds_read_b128 v[30:33], v233 offset:32
	ds_read_b128 v[34:37], v233 offset:16896
	ds_read_b128 v[86:89], v233 offset:16928
	s_waitcnt vmcnt(3) lgkmcnt(3)
	v_mfma_f32_32x32x16_bf16 v[50:65], v[4:7], v[132:135], 0
	s_waitcnt vmcnt(2)
	v_mfma_f32_32x32x16_bf16 v[66:81], v[4:7], v[142:145], 0
	v_and_b32_e32 v5, 64, v223
	v_xor_b32_e32 v4, 1, v223
	v_add_u32_e32 v5, 64, v5
	v_cmp_lt_i32_e32 vcc, v4, v5
	s_nop 1
	v_cndmask_b32_e32 v4, v223, v4, vcc
	s_waitcnt lgkmcnt(1)
	v_mfma_f32_32x32x16_bf16 v[6:21], v[34:37], v[132:135], 0
	v_mfma_f32_32x32x16_bf16 v[34:49], v[34:37], v[142:145], 0
	s_waitcnt vmcnt(3)
	v_mfma_f32_32x32x16_bf16 v[50:65], v[30:33], v[146:149], v[50:65]
	s_waitcnt vmcnt(2)
	v_mfma_f32_32x32x16_bf16 v[66:81], v[30:33], v[150:153], v[66:81]
	s_waitcnt lgkmcnt(0)
	v_mfma_f32_32x32x16_bf16 v[6:21], v[86:89], v[146:149], v[6:21]
	ds_read_b128 v[26:29], v233 offset:64
	v_mfma_f32_32x32x16_bf16 v[34:49], v[86:89], v[150:153], v[34:49]
	ds_read_b128 v[82:85], v233 offset:96
	s_waitcnt vmcnt(3) lgkmcnt(1)
	v_mfma_f32_32x32x16_bf16 v[50:65], v[26:29], v[158:161], v[50:65]
	s_waitcnt vmcnt(2)
	v_mfma_f32_32x32x16_bf16 v[66:81], v[26:29], v[162:165], v[66:81]
	ds_read_b128 v[26:29], v233 offset:16960
	ds_read_b128 v[90:93], v233 offset:16992
	s_waitcnt lgkmcnt(1)
	v_mfma_f32_32x32x16_bf16 v[6:21], v[26:29], v[158:161], v[6:21]
	v_mfma_f32_32x32x16_bf16 v[34:49], v[26:29], v[162:165], v[34:49]
	ds_read_b128 v[22:25], v233 offset:128
	s_waitcnt vmcnt(3)
	v_mfma_f32_32x32x16_bf16 v[50:65], v[82:85], v[166:169], v[50:65]
	s_waitcnt vmcnt(2)
	v_mfma_f32_32x32x16_bf16 v[66:81], v[82:85], v[170:173], v[66:81]
	ds_read_b128 v[82:85], v233 offset:160
	s_waitcnt lgkmcnt(2)
	v_mfma_f32_32x32x16_bf16 v[6:21], v[90:93], v[166:169], v[6:21]
	v_mfma_f32_32x32x16_bf16 v[34:49], v[90:93], v[170:173], v[34:49]
	ds_read_b128 v[90:93], v233 offset:17024
	ds_read_b128 v[94:97], v233 offset:17056
	s_waitcnt vmcnt(4) lgkmcnt(3)
	v_mfma_f32_32x32x16_bf16 v[50:65], v[22:25], v[174:177], v[50:65]
	s_waitcnt vmcnt(3)
	v_mfma_f32_32x32x16_bf16 v[66:81], v[22:25], v[182:185], v[66:81]
	s_waitcnt lgkmcnt(1)
	v_mfma_f32_32x32x16_bf16 v[6:21], v[90:93], v[174:177], v[6:21]
	v_mfma_f32_32x32x16_bf16 v[34:49], v[90:93], v[182:185], v[34:49]
	s_waitcnt vmcnt(5)
	v_mfma_f32_32x32x16_bf16 v[50:65], v[82:85], v[186:189], v[50:65]
	s_waitcnt vmcnt(4)
	v_mfma_f32_32x32x16_bf16 v[66:81], v[82:85], v[138:141], v[66:81]
	ds_read_b128 v[82:85], v233 offset:192
	ds_read_b128 v[218:221], v233 offset:224
	s_waitcnt lgkmcnt(2)
	v_mfma_f32_32x32x16_bf16 v[6:21], v[94:97], v[186:189], v[6:21]
	ds_read_b128 v[210:213], v233 offset:17088
	ds_read_b128 v[30:33], v233 offset:17120
	ds_read_b128 v[198:201], v233 offset:256
	ds_read_b128 v[178:181], v233 offset:288
	ds_read_b128 v[202:205], v233 offset:17152
	ds_read_b128 v[154:157], v233 offset:17184
	global_load_dwordx4 v[214:217], v[228:229], off
	global_load_dwordx4 v[174:177], v[228:229], off offset:32
	global_load_dwordx4 v[206:209], v[230:231], off
	global_load_dwordx4 v[166:169], v[230:231], off offset:32
	ds_read_b128 v[162:165], v233 offset:320
	ds_read_b128 v[146:149], v233 offset:352
	ds_read_b128 v[182:185], v233 offset:17216
	ds_read_b128 v[122:125], v233 offset:17248
	global_load_dwordx4 v[194:197], v[228:229], off offset:64
	global_load_dwordx4 v[142:145], v[228:229], off offset:96
	global_load_dwordx4 v[186:189], v[230:231], off offset:64
	global_load_dwordx4 v[134:137], v[230:231], off offset:96
	ds_read_b128 v[130:133], v233 offset:384
	ds_read_b128 v[114:117], v233 offset:416
	ds_read_b128 v[150:153], v233 offset:17280
	ds_read_b128 v[98:101], v233 offset:17312
	global_load_dwordx4 v[170:173], v[228:229], off offset:128
	global_load_dwordx4 v[110:113], v[228:229], off offset:160
	global_load_dwordx4 v[158:161], v[230:231], off offset:128
	global_load_dwordx4 v[106:109], v[230:231], off offset:160
	v_mfma_f32_32x32x16_bf16 v[34:49], v[94:97], v[138:141], v[34:49]
	s_waitcnt vmcnt(14) lgkmcnt(14)
	v_mfma_f32_32x32x16_bf16 v[50:65], v[82:85], v[238:241], v[50:65]
	s_waitcnt vmcnt(13)
	v_mfma_f32_32x32x16_bf16 v[66:81], v[82:85], v[242:245], v[66:81]
	ds_read_b128 v[102:105], v233 offset:448
	ds_read_b128 v[94:97], v233 offset:480
	ds_read_b128 v[118:121], v233 offset:17344
	ds_read_b128 v[82:85], v233 offset:17376
	global_load_dwordx4 v[138:141], v[228:229], off offset:192
	global_load_dwordx4 v[90:93], v[228:229], off offset:224
	global_load_dwordx4 v[126:129], v[230:231], off offset:192
	global_load_dwordx4 v[86:89], v[230:231], off offset:224
	s_waitcnt lgkmcnt(0)
	s_barrier
; #define MFMA(a, b, c) __builtin_amdgcn_mfma_f32_32x32x16_bf16((a), (b), (c), 0, 0, 0)
; DI void phase_peer_query(const Params& p, char* lds) {
;     ...
;       for (int kk = 0; kk < 8; ++kk) {
;         const bf16x8 a0 = ldfrag(Ct + (wm * 64 + l31) * CT_LD + pp * 128 + kk * 16 + 8 * hh), a1 = ldfrag(Ct + (wm * 64 + 32 + l31) * CT_LD + pp * 128 + kk * 16 + 8 * hh);
;         const bf16x8 b0 = ldfrag(SK + (size_t)(pp * 128 + wn * 64 + l31) * 128 + kk * 16 + 8 * hh), b1 = ldfrag(SK + (size_t)(pp * 128 + wn * 64 + 32 + l31) * 128 + kk * 16 + 8 * hh);
;         sacc[pp][0][0] = MFMA(a0, b0, sacc[pp][0][0]); sacc[pp][0][1] = MFMA(a0, b1, sacc[pp][0][1]);
;         sacc[pp][1][0] = MFMA(a1, b0, sacc[pp][1][0]); sacc[pp][1][1] = MFMA(a1, b1, sacc[pp][1][1]);
;       }
;     }
;     __syncthreads();
; #pragma unroll
;     for (int pp = 0; pp < 2; ++pp) {
;       const int hp = hq * 2 + pp;
; #pragma unroll
;       for (int i = 0; i < 2; ++i)
; #pragma unroll
;         for (int j = 0; j < 2; ++j)
; #pragma unroll
;           for (int r = 0; r < 16; ++r)
;             Sc[(wm * 64 + i * 32 + (r & 3) + 8 * (r >> 2) + 4 * hh) * 132 + wn * 64 + j * 32 + l31] = sacc[pp][i][j][r];
;       __syncthreads();
;     ...
;         {
;           float kq[4][16];
; #pragma unroll
;           for (int gq = 0; gq < 4; ++gq) {
; #pragma unroll
;             for (int e4 = 0; e4 < 4; ++e4) {
;               const float4 s4 = *(const float4*)(srow + 16 * gq + 4 * e4);
;               const float sv[4] = {s4.x, s4.y, s4.z, s4.w};
; #pragma unroll
;               for (int u = 0; u < 4; ++u)
;                 kq[gq][4 * e4 + u] = __uint_as_float((__float_as_uint(sv[u]) & 0xFFFFFF80u) | (unsigned)(127 - (half * 64 + 16 * gq + 4 * e4 + u)));
;             }
	v_mfma_f32_32x32x16_bf16 v[6:21], v[210:213], v[238:241], v[6:21]
	v_mfma_f32_32x32x16_bf16 v[34:49], v[210:213], v[242:245], v[34:49]
	v_add_u32_e32 v210, 0x7600, v236
	v_mfma_f32_32x32x16_bf16 v[50:65], v[218:221], v[246:249], v[50:65]
	s_waitcnt vmcnt(16)
	v_mfma_f32_32x32x16_bf16 v[66:81], v[218:221], v[252:255], v[66:81]
	s_nop 11
	ds_write2_b32 v236, v50, v66 offset1:32
	ds_write2_b32 v236, v51, v67 offset0:132 offset1:164
	v_mfma_f32_32x32x16_bf16 v[6:21], v[30:33], v[246:249], v[6:21]
	v_add_u32_e32 v66, 0x400, v236
	ds_write2_b32 v66, v52, v68 offset0:8 offset1:40
	ds_write2_b32 v66, v53, v69 offset0:140 offset1:172
	v_add_u32_e32 v67, 0x1000, v236
	v_add_u32_e32 v68, 0x1400, v236
	v_add_u32_e32 v69, 0x2000, v236
	ds_write2_b32 v67, v54, v70 offset0:32 offset1:64
	ds_write2_b32 v67, v55, v71 offset0:164 offset1:196
	ds_write2_b32 v68, v56, v72 offset0:40 offset1:72
	ds_write2_b32 v68, v57, v73 offset0:172 offset1:204
	v_mfma_f32_32x32x16_bf16 v[34:49], v[30:33], v[252:255], v[34:49]
	ds_write2_b32 v69, v58, v74 offset0:64 offset1:96
	ds_write2_b32 v69, v59, v75 offset0:196 offset1:228
	v_add_u32_e32 v70, 0x2400, v236
	v_add_u32_e32 v71, 0x3000, v236
	v_add_u32_e32 v72, 0x3200, v236
	v_add_u32_e32 v73, 0x3400, v236
	v_add_u32_e32 v74, 0x3600, v236
	ds_write2_b32 v70, v60, v76 offset0:72 offset1:104
	ds_write2_b32 v70, v61, v77 offset0:204 offset1:236
	ds_write2_b32 v71, v62, v78 offset0:96 offset1:128
	ds_write2_b32 v72, v63, v79 offset0:100 offset1:132
	ds_write2_b32 v73, v64, v80 offset0:104 offset1:136
	ds_write2_b32 v74, v65, v81 offset0:108 offset1:140
	v_add_u32_e32 v75, 0x4000, v236
	v_add_u32_e32 v76, 0x4400, v236
	v_add_u32_e32 v77, 0x4800, v236
	v_add_u32_e32 v78, 0x5000, v236
	v_add_u32_e32 v79, 0x5400, v236
	v_add_u32_e32 v80, 0x5800, v236
	v_add_u32_e32 v81, 0x6000, v236
	v_add_u32_e32 v190, 0x6400, v236
	v_add_u32_e32 v191, 0x6800, v236
	v_add_u32_e32 v192, 0x7200, v236
	v_add_u32_e32 v193, 0x7400, v236
	v_lshlrev_b32_e32 v218, 2, v4
	ds_write2_b32 v75, v6, v34 offset0:128 offset1:160
	ds_write2_b32 v76, v7, v35 offset0:4 offset1:36
	ds_write2_b32 v76, v8, v36 offset0:136 offset1:168
	ds_write2_b32 v77, v9, v37 offset0:12 offset1:44
	ds_write2_b32 v78, v10, v38 offset0:160 offset1:192
	ds_write2_b32 v79, v11, v39 offset0:36 offset1:68
	ds_write2_b32 v79, v12, v40 offset0:168 offset1:200
	ds_write2_b32 v80, v13, v41 offset0:44 offset1:76
	ds_write2_b32 v81, v14, v42 offset0:192 offset1:224
	ds_write2_b32 v190, v15, v43 offset0:68 offset1:100
	ds_write2_b32 v190, v16, v44 offset0:200 offset1:232
	s_waitcnt vmcnt(15)
	v_mfma_f32_32x32x16_bf16 v[0:15], v[198:201], v[214:217], 0
	ds_write2_b32 v191, v17, v45 offset0:76 offset1:108
	ds_write2_b32 v192, v18, v46 offset0:96 offset1:128
	ds_write2_b32 v193, v19, v47 offset0:100 offset1:132
	ds_write2_b32 v210, v20, v48 offset0:104 offset1:136
	v_add_u32_e32 v64, s6, v232
	s_lshl_b32 s6, s49, 5
	s_waitcnt vmcnt(13)
	v_mfma_f32_32x32x16_bf16 v[32:47], v[198:201], v[206:209], 0
	v_add_u32_e32 v198, 0x7800, v236
	ds_write2_b32 v198, v21, v49 offset0:108 offset1:140
	s_waitcnt lgkmcnt(0)
	s_barrier
	ds_read_b128 v[238:241], v235
	s_waitcnt lgkmcnt(0)
	v_and_b32_e32 v48, 0xffffff80, v238
	v_bitop3_b32 v65, v234, s48, v48 bitop3:0x36
	v_mfma_f32_32x32x16_bf16 v[48:63], v[202:205], v[206:209], 0
	v_and_b32_e32 v199, 0xffffff80, v239
	v_sub_u32_e32 v199, v199, v234
	v_and_b32_e32 v200, 0xffffff80, v240
	v_and_b32_e32 v201, 0xffffff80, v241
	v_add_u32_e32 v199, 0x7e, v199
	v_sub_u32_e32 v200, v200, v234
	v_sub_u32_e32 v201, v201, v234
	v_mfma_f32_32x32x16_bf16 v[16:31], v[202:205], v[214:217], 0
	ds_read_b128 v[212:215], v235 offset:16
	ds_read_b128 v[242:245], v235 offset:32
	ds_read_b128 v[246:249], v235 offset:48
	v_add_u32_e32 v200, 0x7d, v200
	v_add_u32_e32 v201, 0x7c, v201
	s_waitcnt lgkmcnt(2)
	v_and_b32_e32 v202, 0xffffff80, v212
	v_and_b32_e32 v203, 0xffffff80, v213
	v_sub_u32_e32 v202, v202, v234
	v_sub_u32_e32 v203, v203, v234
	s_waitcnt vmcnt(12)
	v_mfma_f32_32x32x16_bf16 v[32:47], v[178:181], v[166:169], v[32:47]
	v_max_f32_e32 v65, v65, v65
	v_add_u32_e32 v202, 0x7b, v202
	v_add_u32_e32 v203, 0x7a, v203
	v_mfma_f32_32x32x16_bf16 v[48:63], v[154:157], v[166:169], v[48:63]
	s_waitcnt lgkmcnt(0)
	v_and_b32_e32 v166, 0xffffff80, v248
	v_and_b32_e32 v167, 0xffffff80, v249
	v_sub_u32_e32 v166, v166, v234
	v_max_f32_e32 v168, v202, v202
	v_add_u32_e32 v166, 0x71, v166
	v_mfma_f32_32x32x16_bf16 v[0:15], v[178:181], v[174:177], v[0:15]
	v_and_b32_e32 v178, 0xffffff80, v214
	v_and_b32_e32 v179, 0xffffff80, v215
	v_and_b32_e32 v180, 0xffffff80, v242
	v_sub_u32_e32 v178, v178, v234
	v_sub_u32_e32 v179, v179, v234
	v_add_u32_e32 v178, 0x79, v178
	v_add_u32_e32 v179, 0x78, v179
	v_mfma_f32_32x32x16_bf16 v[16:31], v[154:157], v[174:177], v[16:31]
	v_and_b32_e32 v175, 0xffffff80, v243
	v_and_b32_e32 v176, 0xffffff80, v244
	v_and_b32_e32 v155, 0xffffff80, v245
	v_sub_u32_e32 v174, v180, v234
	v_sub_u32_e32 v175, v175, v234
	v_sub_u32_e32 v176, v176, v234
	v_sub_u32_e32 v155, v155, v234
	s_waitcnt vmcnt(9)
; #define MFMA(a, b, c) __builtin_amdgcn_mfma_f32_32x32x16_bf16((a), (b), (c), 0, 0, 0)
; DI void phase_peer_query(const Params& p, char* lds) {
;     ...
;       for (int kk = 0; kk < 8; ++kk) {
;         const bf16x8 a0 = ldfrag(Ct + (wm * 64 + l31) * CT_LD + pp * 128 + kk * 16 + 8 * hh), a1 = ldfrag(Ct + (wm * 64 + 32 + l31) * CT_LD + pp * 128 + kk * 16 + 8 * hh);
;         const bf16x8 b0 = ldfrag(SK + (size_t)(pp * 128 + wn * 64 + l31) * 128 + kk * 16 + 8 * hh), b1 = ldfrag(SK + (size_t)(pp * 128 + wn * 64 + 32 + l31) * 128 + kk * 16 + 8 * hh);
;         sacc[pp][0][0] = MFMA(a0, b0, sacc[pp][0][0]); sacc[pp][0][1] = MFMA(a0, b1, sacc[pp][0][1]);
;         sacc[pp][1][0] = MFMA(a1, b0, sacc[pp][1][0]); sacc[pp][1][1] = MFMA(a1, b1, sacc[pp][1][1]);
;     ...
;           for (int gq = 0; gq < 4; ++gq) {
; #pragma unroll
;             for (int e4 = 0; e4 < 4; ++e4) {
;               const float4 s4 = *(const float4*)(srow + 16 * gq + 4 * e4);
;               const float sv[4] = {s4.x, s4.y, s4.z, s4.w};
; #pragma unroll
;               for (int u = 0; u < 4; ++u)
;                 kq[gq][4 * e4 + u] = __uint_as_float((__float_as_uint(sv[u]) & 0xFFFFFF80u) | (unsigned)(127 - (half * 64 + 16 * gq + 4 * e4 + u)));
;             }
; #pragma unroll
;             for (int kk2 = 2; kk2 <= 16; kk2 <<= 1)
; #pragma unroll
;               for (int j = kk2 >> 1; j > 0; j >>= 1)
; #pragma unroll
;                 for (int i = 0; i < 16; ++i) {
;                   const int l = i ^ j;
;                   if (l > i) {
;                     const float hi = fmaxf(kq[gq][i], kq[gq][l]), lo = fminf(kq[gq][i], kq[gq][l]);
;                     const bool desc = (i & kk2) == 0;
;                     kq[gq][i] = desc ? hi : lo; kq[gq][l] = desc ? lo : hi;
;                   }
;                 }
;           }
	v_mfma_f32_32x32x16_bf16 v[32:47], v[162:165], v[186:189], v[32:47]
	v_and_b32_e32 v156, 0xffffff80, v246
	v_and_b32_e32 v157, 0xffffff80, v247
	v_add_u32_e32 v174, 0x77, v174
	v_add_u32_e32 v175, 0x76, v175
	v_add_u32_e32 v154, 0x75, v176
	v_add_u32_e32 v155, 0x74, v155
	v_sub_u32_e32 v156, v156, v234
	v_mfma_f32_32x32x16_bf16 v[48:63], v[182:185], v[186:189], v[48:63]
	v_sub_u32_e32 v157, v157, v234
	v_add_u32_e32 v156, 0x73, v156
	v_add_u32_e32 v157, 0x72, v157
	v_max_f32_e32 v176, v178, v178
	v_max_f32_e32 v175, v175, v175
	v_max_f32_e32 v174, v174, v174
	v_max_f32_e32 v155, v155, v155
	v_mfma_f32_32x32x16_bf16 v[0:15], v[162:165], v[194:197], v[0:15]
	v_max_f32_e32 v163, v199, v199
	v_max_f32_e32 v164, v65, v163
	v_min_f32_e32 v65, v65, v163
	v_max_f32_e32 v163, v201, v201
	v_max_f32_e32 v165, v200, v200
	v_sub_u32_e32 v162, v167, v234
	v_max_f32_e32 v167, v165, v163
	v_mfma_f32_32x32x16_bf16 v[16:31], v[182:185], v[194:197], v[16:31]
	v_min_f32_e32 v163, v165, v163
	v_max_f32_e32 v165, v203, v203
	v_add_u32_e32 v162, 0x70, v162
	v_max_f32_e32 v169, v168, v165
	v_min_f32_e32 v165, v168, v165
	v_max_f32_e32 v168, v179, v179
	v_max_f32_e32 v154, v154, v154
	s_waitcnt vmcnt(8)
	v_mfma_f32_32x32x16_bf16 v[32:47], v[146:149], v[134:137], v[32:47]
	v_max_f32_e32 v177, v176, v168
	v_min_f32_e32 v168, v176, v168
	v_max_f32_e32 v176, v174, v175
	v_min_f32_e32 v174, v174, v175
	v_max_f32_e32 v175, v154, v155
	v_min_f32_e32 v154, v154, v155
	v_max_f32_e32 v155, v157, v157
	v_mfma_f32_32x32x16_bf16 v[48:63], v[122:125], v[134:137], v[48:63]
	v_max_f32_e32 v156, v156, v156
	v_min_f32_e32 v157, v165, v177
	v_mfma_f32_32x32x16_bf16 v[0:15], v[146:149], v[142:145], v[0:15]
	v_max_f32_e32 v148, v162, v162
	v_max_f32_e32 v149, v166, v166
	v_max_f32_e32 v146, v156, v155
	v_min_f32_e32 v147, v156, v155
	v_max_f32_e32 v155, v149, v148
	v_min_f32_e32 v148, v149, v148
	v_max_f32_e32 v149, v164, v163
	v_mfma_f32_32x32x16_bf16 v[16:31], v[122:125], v[142:145], v[16:31]
	v_min_f32_e32 v142, v164, v163
	v_max_f32_e32 v143, v65, v167
	v_min_f32_e32 v65, v65, v167
	v_max_f32_e32 v144, v169, v168
	v_min_f32_e32 v145, v169, v168
	v_max_f32_e32 v156, v165, v177
	v_max_f32_e32 v122, v176, v154
	s_waitcnt vmcnt(5)
	v_mfma_f32_32x32x16_bf16 v[32:47], v[130:133], v[158:161], v[32:47]
	v_min_f32_e32 v123, v176, v154
	v_max_f32_e32 v124, v174, v175
	v_min_f32_e32 v125, v174, v175
	v_max_f32_e32 v134, v146, v148
	v_min_f32_e32 v135, v146, v148
	v_max_f32_e32 v136, v147, v155
	v_min_f32_e32 v137, v147, v155
	v_mfma_f32_32x32x16_bf16 v[48:63], v[150:153], v[158:161], v[48:63]
	v_max_f32_e32 v146, v149, v143
	v_min_f32_e32 v143, v149, v143
	v_max_f32_e32 v147, v142, v65
	v_min_f32_e32 v65, v142, v65
	v_max_f32_e32 v142, v145, v157
	v_min_f32_e32 v145, v145, v157
	v_mfma_f32_32x32x16_bf16 v[0:15], v[130:133], v[170:173], v[0:15]
	v_max_f32_e32 v130, v144, v156
	v_min_f32_e32 v131, v144, v156
	v_max_f32_e32 v132, v122, v124
	v_min_f32_e32 v122, v122, v124
	v_max_f32_e32 v124, v123, v125
	v_min_f32_e32 v123, v123, v125
	v_max_f32_e32 v125, v135, v137
	v_mfma_f32_32x32x16_bf16 v[16:31], v[150:153], v[170:173], v[16:31]
	v_min_f32_e32 v133, v135, v137
	v_max_f32_e32 v135, v134, v136
	v_min_f32_e32 v134, v134, v136
	v_max_f32_e32 v136, v146, v145
	v_min_f32_e32 v137, v146, v145
	v_max_f32_e32 v144, v143, v142
	v_min_f32_e32 v142, v143, v142
	s_waitcnt vmcnt(4)
	v_mfma_f32_32x32x16_bf16 v[32:47], v[114:117], v[106:109], v[32:47]
	v_max_f32_e32 v143, v147, v131
	v_min_f32_e32 v131, v147, v131
	v_max_f32_e32 v145, v65, v130
	v_min_f32_e32 v65, v65, v130
	v_max_f32_e32 v130, v132, v133
	v_min_f32_e32 v132, v132, v133
	v_max_f32_e32 v133, v122, v125
	v_mfma_f32_32x32x16_bf16 v[48:63], v[98:101], v[106:109], v[48:63]
	v_min_f32_e32 v122, v122, v125
	v_max_f32_e32 v125, v124, v134
	v_min_f32_e32 v124, v124, v134
	v_max_f32_e32 v134, v123, v135
	v_min_f32_e32 v123, v123, v135
	v_max_f32_e32 v135, v136, v143
	v_min_f32_e32 v136, v136, v143
	v_mfma_f32_32x32x16_bf16 v[0:15], v[114:117], v[110:113], v[0:15]
	v_max_f32_e32 v116, v137, v131
	v_min_f32_e32 v117, v137, v131
	v_max_f32_e32 v131, v142, v65
	v_max_f32_e32 v137, v132, v124
	v_max_f32_e32 v106, v116, v131
	v_min_f32_e32 v107, v116, v131
	v_max_f32_e32 v114, v144, v145
	v_mfma_f32_32x32x16_bf16 v[16:31], v[98:101], v[110:113], v[16:31]
	v_min_f32_e32 v110, v132, v124
	v_max_f32_e32 v111, v122, v123
	v_min_f32_e32 v112, v122, v123
	v_max_f32_e32 v113, v130, v125
	v_min_f32_e32 v122, v130, v125
	v_max_f32_e32 v123, v133, v134
	v_min_f32_e32 v124, v133, v134
	ds_read_b128 v[130:133], v235 offset:128
	v_min_f32_e32 v115, v144, v145
	v_max_f32_e32 v98, v135, v114
	v_min_f32_e32 v99, v135, v114
	v_max_f32_e32 v100, v136, v115
	v_min_f32_e32 v101, v136, v115
	v_max_f32_e32 v109, v110, v112
	v_min_f32_e32 v110, v110, v112
	v_max_f32_e32 v112, v137, v111
	v_min_f32_e32 v111, v137, v111
	s_waitcnt vmcnt(1)
	v_mfma_f32_32x32x16_bf16 v[32:47], v[102:105], v[126:129], v[32:47]
	ds_read_b128 v[134:137], v235 offset:144
	v_min_f32_e32 v65, v142, v65
	v_max_f32_e32 v108, v117, v65
	v_min_f32_e32 v65, v117, v65
	v_max_f32_e32 v114, v122, v124
	v_min_f32_e32 v115, v122, v124
	v_mfma_f32_32x32x16_bf16 v[48:63], v[118:121], v[126:129], v[48:63]
	s_waitcnt lgkmcnt(1)
; DI void phase_peer_query(const Params& p, char* lds) {
;     ...
;           for (int gq = 0; gq < 4; ++gq) {
; #pragma unroll
;             for (int e4 = 0; e4 < 4; ++e4) {
;               const float4 s4 = *(const float4*)(srow + 16 * gq + 4 * e4);
;               const float sv[4] = {s4.x, s4.y, s4.z, s4.w};
; #pragma unroll
;               for (int u = 0; u < 4; ++u)
;                 kq[gq][4 * e4 + u] = __uint_as_float((__float_as_uint(sv[u]) & 0xFFFFFF80u) | (unsigned)(127 - (half * 64 + 16 * gq + 4 * e4 + u)));
;             }
; #pragma unroll
;             for (int kk2 = 2; kk2 <= 16; kk2 <<= 1)
; #pragma unroll
;               for (int j = kk2 >> 1; j > 0; j >>= 1)
; #pragma unroll
;                 for (int i = 0; i < 16; ++i) {
;                   const int l = i ^ j;
;                   if (l > i) {
;                     const float hi = fmaxf(kq[gq][i], kq[gq][l]), lo = fminf(kq[gq][i], kq[gq][l]);
;                     const bool desc = (i & kk2) == 0;
;                     kq[gq][i] = desc ? hi : lo; kq[gq][l] = desc ? lo : hi;
;                   }
;                 }
;           }
	v_and_b32_e32 v129, 0xffffff80, v130
	v_and_b32_e32 v130, 0xffffff80, v131
	v_sub_u32_e32 v130, v130, v234
	v_sub_u32_e32 v129, v129, v234
	v_add_u32_e32 v129, 0x5f, v129
	v_max_f32_e32 v129, v129, v129
	v_mfma_f32_32x32x16_bf16 v[0:15], v[102:105], v[138:141], v[0:15]
	v_max_f32_e32 v102, v113, v123
	v_min_f32_e32 v103, v113, v123
	v_max_f32_e32 v104, v98, v110
	v_min_f32_e32 v98, v98, v110
	v_max_f32_e32 v105, v99, v109
	v_min_f32_e32 v99, v99, v109
	v_max_f32_e32 v109, v100, v111
	v_mfma_f32_32x32x16_bf16 v[16:31], v[118:121], v[138:141], v[16:31]
	v_add_u32_e32 v138, 0x5e, v130
	v_and_b32_e32 v130, 0xffffff80, v132
	v_sub_u32_e32 v130, v130, v234
	v_add_u32_e32 v139, 0x5d, v130
	v_and_b32_e32 v130, 0xffffff80, v133
	v_sub_u32_e32 v130, v130, v234
	v_add_u32_e32 v140, 0x5c, v130
	s_waitcnt lgkmcnt(0)
	v_and_b32_e32 v130, 0xffffff80, v134
	v_sub_u32_e32 v130, v130, v234
	v_add_u32_e32 v141, 0x5b, v130
	v_and_b32_e32 v130, 0xffffff80, v135
	v_sub_u32_e32 v130, v130, v234
	v_add_u32_e32 v142, 0x5a, v130
	v_and_b32_e32 v130, 0xffffff80, v136
	v_sub_u32_e32 v130, v130, v234
	v_add_u32_e32 v143, 0x59, v130
	ds_read_b128 v[130:133], v235 offset:160
	v_and_b32_e32 v134, 0xffffff80, v137
	v_sub_u32_e32 v134, v134, v234
	v_add_u32_e32 v144, 0x58, v134
	ds_read_b128 v[134:137], v235 offset:176
	s_waitcnt lgkmcnt(1)
	v_and_b32_e32 v130, 0xffffff80, v130
	v_and_b32_e32 v131, 0xffffff80, v131
	v_max_f32_e32 v138, v138, v138
	v_sub_u32_e32 v130, v130, v234
	v_sub_u32_e32 v131, v131, v234
	v_and_b32_e32 v132, 0xffffff80, v132
	v_and_b32_e32 v133, 0xffffff80, v133
	v_max_f32_e32 v145, v129, v138
	v_min_f32_e32 v129, v129, v138
	v_max_f32_e32 v138, v140, v140
	v_max_f32_e32 v139, v139, v139
	v_add_u32_e32 v130, 0x57, v130
	v_add_u32_e32 v131, 0x56, v131
	v_sub_u32_e32 v132, v132, v234
	v_sub_u32_e32 v133, v133, v234
	s_waitcnt lgkmcnt(0)
	v_and_b32_e32 v134, 0xffffff80, v134
	v_and_b32_e32 v135, 0xffffff80, v135
	v_max_f32_e32 v140, v139, v138
	v_min_f32_e32 v138, v139, v138
	v_max_f32_e32 v139, v142, v142
	v_max_f32_e32 v141, v141, v141
	v_add_u32_e32 v132, 0x55, v132
	v_add_u32_e32 v133, 0x54, v133
	v_sub_u32_e32 v134, v134, v234
	v_sub_u32_e32 v135, v135, v234
	v_and_b32_e32 v136, 0xffffff80, v136
	v_and_b32_e32 v137, 0xffffff80, v137
	v_max_f32_e32 v142, v141, v139
	v_min_f32_e32 v139, v141, v139
	v_max_f32_e32 v141, v144, v144
	v_max_f32_e32 v143, v143, v143
	v_max_f32_e32 v131, v131, v131
	v_max_f32_e32 v130, v130, v130
	v_add_u32_e32 v134, 0x53, v134
	v_add_u32_e32 v135, 0x52, v135
	v_sub_u32_e32 v136, v136, v234
	v_sub_u32_e32 v137, v137, v234
	v_max_f32_e32 v144, v143, v141
	v_min_f32_e32 v141, v143, v141
	v_max_f32_e32 v143, v130, v131
	v_min_f32_e32 v130, v130, v131
	v_max_f32_e32 v131, v133, v133
	v_max_f32_e32 v132, v132, v132
	v_add_u32_e32 v136, 0x51, v136
	v_add_u32_e32 v137, 0x50, v137
	v_max_f32_e32 v133, v132, v131
	v_min_f32_e32 v131, v132, v131
	v_max_f32_e32 v132, v135, v135
	v_max_f32_e32 v134, v134, v134
	v_max_f32_e32 v135, v134, v132
	v_min_f32_e32 v132, v134, v132
	v_max_f32_e32 v134, v137, v137
	v_max_f32_e32 v136, v136, v136
	v_max_f32_e32 v137, v136, v134
	v_min_f32_e32 v134, v136, v134
	v_max_f32_e32 v136, v145, v138
	v_min_f32_e32 v138, v145, v138
	v_max_f32_e32 v145, v129, v140
	v_min_f32_e32 v129, v129, v140
	v_max_f32_e32 v140, v142, v141
	v_min_f32_e32 v141, v142, v141
	v_max_f32_e32 v142, v139, v144
	v_min_f32_e32 v139, v139, v144
	v_max_f32_e32 v144, v143, v131
	v_min_f32_e32 v131, v143, v131
	v_max_f32_e32 v143, v130, v133
	v_min_f32_e32 v130, v130, v133
	v_max_f32_e32 v133, v135, v134
	v_min_f32_e32 v134, v135, v134
	v_max_f32_e32 v135, v132, v137
	v_min_f32_e32 v132, v132, v137
	v_max_f32_e32 v137, v136, v145
	v_min_f32_e32 v136, v136, v145
	v_max_f32_e32 v145, v138, v129
	v_min_f32_e32 v129, v138, v129
	v_max_f32_e32 v138, v141, v139
	v_min_f32_e32 v139, v141, v139
	v_max_f32_e32 v141, v140, v142
	v_min_f32_e32 v140, v140, v142
	v_max_f32_e32 v142, v144, v143
	v_min_f32_e32 v143, v144, v143
	v_max_f32_e32 v144, v131, v130
	v_min_f32_e32 v130, v131, v130
	v_max_f32_e32 v131, v134, v132
	v_min_f32_e32 v132, v134, v132
	v_max_f32_e32 v134, v133, v135
	v_min_f32_e32 v133, v133, v135
	v_max_f32_e32 v135, v137, v139
	v_min_f32_e32 v137, v137, v139
	v_max_f32_e32 v139, v136, v138
	v_min_f32_e32 v136, v136, v138
	v_max_f32_e32 v138, v145, v140
	v_min_f32_e32 v140, v145, v140
	v_max_f32_e32 v145, v129, v141
	v_min_f32_e32 v129, v129, v141
	v_max_f32_e32 v141, v142, v132
	v_min_f32_e32 v132, v142, v132
	v_max_f32_e32 v142, v143, v131
	v_min_f32_e32 v131, v143, v131
	v_max_f32_e32 v143, v144, v133
	v_min_f32_e32 v133, v144, v133
	v_max_f32_e32 v144, v130, v134
	v_min_f32_e32 v130, v130, v134
	v_max_f32_e32 v134, v135, v138
	v_min_f32_e32 v135, v135, v138
	v_max_f32_e32 v138, v139, v145
	v_min_f32_e32 v139, v139, v145
	v_max_f32_e32 v145, v137, v140
	v_min_f32_e32 v137, v137, v140
	v_max_f32_e32 v140, v136, v129
	v_min_f32_e32 v129, v136, v129
	v_max_f32_e32 v136, v132, v133
	v_min_f32_e32 v132, v132, v133
	v_max_f32_e32 v133, v131, v130
	v_min_f32_e32 v130, v131, v130
	v_max_f32_e32 v131, v141, v143
	v_min_f32_e32 v141, v141, v143
	v_max_f32_e32 v143, v142, v144
	v_min_f32_e32 v142, v142, v144
	v_max_f32_e32 v144, v134, v138
	v_min_f32_e32 v134, v134, v138
	v_max_f32_e32 v138, v135, v139
	v_min_f32_e32 v135, v135, v139
	v_max_f32_e32 v139, v145, v140
	v_min_f32_e32 v140, v145, v140
	v_max_f32_e32 v145, v137, v129
	v_min_f32_e32 v129, v137, v129
	v_max_f32_e32 v137, v132, v130
	v_min_f32_e32 v130, v132, v130
	v_max_f32_e32 v132, v136, v133
	v_min_f32_e32 v133, v136, v133
	v_max_f32_e32 v136, v141, v142
; DI void phase_peer_query(const Params& p, char* lds) {
;     ...
;           for (int gq = 0; gq < 4; ++gq) {
; #pragma unroll
;             for (int e4 = 0; e4 < 4; ++e4) {
;               const float4 s4 = *(const float4*)(srow + 16 * gq + 4 * e4);
;               const float sv[4] = {s4.x, s4.y, s4.z, s4.w};
; #pragma unroll
;               for (int u = 0; u < 4; ++u)
;                 kq[gq][4 * e4 + u] = __uint_as_float((__float_as_uint(sv[u]) & 0xFFFFFF80u) | (unsigned)(127 - (half * 64 + 16 * gq + 4 * e4 + u)));
;             }
; #pragma unroll
;             for (int kk2 = 2; kk2 <= 16; kk2 <<= 1)
; #pragma unroll
;               for (int j = kk2 >> 1; j > 0; j >>= 1)
; #pragma unroll
;                 for (int i = 0; i < 16; ++i) {
;                   const int l = i ^ j;
;                   if (l > i) {
;                     const float hi = fmaxf(kq[gq][i], kq[gq][l]), lo = fminf(kq[gq][i], kq[gq][l]);
;                     const bool desc = (i & kk2) == 0;
;                     kq[gq][i] = desc ? hi : lo; kq[gq][l] = desc ? lo : hi;
;                   }
;                 }
;           }
; #pragma unroll
;           for (int pr = 0; pr < 2; ++pr) {
; #pragma unroll
;             for (int i = 0; i < 16; ++i) kq[2 * pr][i] = fmaxf(kq[2 * pr][i], kq[2 * pr + 1][15 - i]);
; #pragma unroll
;             for (int d = 8; d >= 1; d >>= 1)
; #pragma unroll
;               for (int i = 0; i < 16; ++i)
;                 if ((i & d) == 0) { const float hi = fmaxf(kq[2 * pr][i], kq[2 * pr][i + d]), lo = fminf(kq[2 * pr][i], kq[2 * pr][i + d]); kq[2 * pr][i] = hi; kq[2 * pr][i + d] = lo; }
;           }
	v_min_f32_e32 v141, v141, v142
	v_max_f32_e32 v142, v131, v143
	v_min_f32_e32 v131, v131, v143
	v_max_f32_e32 v143, v144, v130
	v_min_f32_e32 v130, v144, v130
	v_max_f32_e32 v144, v134, v137
	v_min_f32_e32 v134, v134, v137
	v_max_f32_e32 v137, v138, v133
	v_min_f32_e32 v133, v138, v133
	v_max_f32_e32 v138, v135, v132
	v_min_f32_e32 v132, v135, v132
	v_max_f32_e32 v135, v139, v141
	v_min_f32_e32 v139, v139, v141
	v_max_f32_e32 v141, v140, v136
	v_min_f32_e32 v136, v140, v136
	v_max_f32_e32 v140, v145, v131
	v_min_f32_e32 v131, v145, v131
	v_max_f32_e32 v145, v129, v142
	v_min_f32_e32 v129, v129, v142
	v_max_f32_e32 v142, v143, v135
	v_min_f32_e32 v135, v143, v135
	v_max_f32_e32 v143, v144, v141
	v_min_f32_e32 v141, v144, v141
	v_max_f32_e32 v144, v137, v140
	v_min_f32_e32 v137, v137, v140
	v_max_f32_e32 v140, v138, v145
	v_max_f32_e32 v146, v134, v136
	v_min_f32_e32 v134, v134, v136
	v_max_f32_e32 v136, v133, v131
	v_min_f32_e32 v131, v133, v131
	v_max_f32_e32 v133, v132, v129
	v_min_f32_e32 v132, v132, v129
	v_min_f32_e32 v100, v100, v111
	v_max_f32_e32 v110, v101, v112
	v_min_f32_e32 v101, v101, v112
	v_max_f32_e32 v111, v106, v115
	v_min_f32_e32 v106, v106, v115
	v_max_f32_e32 v112, v107, v114
	v_max_f32_e32 v113, v108, v103
	v_min_f32_e32 v103, v108, v103
	v_max_f32_e32 v108, v65, v102
	v_min_f32_e32 v138, v138, v145
	v_max_f32_e32 v145, v130, v139
	v_min_f32_e32 v139, v130, v139
	v_max_f32_e32 v129, v142, v144
	v_min_f32_e32 v142, v142, v144
	v_max_f32_e32 v130, v143, v140
	v_min_f32_e32 v140, v143, v140
	v_max_f32_e32 v143, v135, v137
	v_min_f32_e32 v144, v135, v137
	v_max_f32_e32 v149, v146, v133
	v_min_f32_e32 v146, v146, v133
	v_max_f32_e32 v151, v134, v132
	v_min_f32_e32 v152, v134, v132
	ds_read_b128 v[132:135], v235 offset:192
	v_min_f32_e32 v107, v107, v114
	v_min_f32_e32 v65, v65, v102
	v_max_f32_e32 v102, v104, v111
	v_min_f32_e32 v104, v104, v111
	v_max_f32_e32 v111, v105, v112
	v_min_f32_e32 v105, v105, v112
	v_max_f32_e32 v112, v109, v113
	v_min_f32_e32 v109, v109, v113
	v_max_f32_e32 v113, v110, v108
	v_min_f32_e32 v108, v110, v108
	v_max_f32_e32 v110, v98, v106
	v_min_f32_e32 v98, v98, v106
	v_max_f32_e32 v106, v100, v103
	v_mfma_f32_32x32x16_bf16 v[0:15], v[94:97], v[90:93], v[0:15]
	v_max_f32_e32 v147, v141, v138
	v_min_f32_e32 v141, v141, v138
	v_max_f32_e32 v148, v145, v136
	v_min_f32_e32 v145, v145, v136
	v_max_f32_e32 v150, v139, v131
	v_min_f32_e32 v131, v139, v131
	ds_read_b128 v[136:139], v235 offset:208
	s_waitcnt vmcnt(0)
	v_mfma_f32_32x32x16_bf16 v[32:47], v[94:97], v[86:89], v[32:47]
	v_max_f32_e32 v97, v99, v107
	v_min_f32_e32 v99, v99, v107
	v_max_f32_e32 v96, v105, v108
	v_min_f32_e32 v95, v105, v108
	s_waitcnt lgkmcnt(1)
	v_and_b32_e32 v132, 0xffffff80, v132
	v_sub_u32_e32 v132, v132, v234
	v_min_f32_e32 v100, v100, v103
	v_mfma_f32_32x32x16_bf16 v[16:31], v[82:85], v[90:93], v[16:31]
	v_max_f32_e32 v93, v104, v109
	v_min_f32_e32 v92, v104, v109
	v_max_f32_e32 v103, v101, v65
	v_min_f32_e32 v101, v101, v65
	v_max_f32_e32 v65, v102, v112
	v_min_f32_e32 v91, v102, v112
	v_max_f32_e32 v90, v111, v113
	v_mfma_f32_32x32x16_bf16 v[48:63], v[82:85], v[86:89], v[48:63]
	v_max_f32_e32 v82, v110, v106
	v_min_f32_e32 v84, v110, v106
	ds_read_b128 v[106:109], v235 offset:64
	v_min_f32_e32 v94, v111, v113
	ds_read_b128 v[110:113], v235 offset:80
	v_add_u32_e32 v161, 0x4f, v132
	v_and_b32_e32 v132, 0xffffff80, v133
	s_waitcnt lgkmcnt(1)
	v_and_b32_e32 v105, 0xffffff80, v106
	v_and_b32_e32 v106, 0xffffff80, v107
	v_sub_u32_e32 v106, v106, v234
	v_sub_u32_e32 v132, v132, v234
	v_add_u32_e32 v114, 0x6e, v106
	v_and_b32_e32 v106, 0xffffff80, v108
	v_add_u32_e32 v162, 0x4e, v132
	v_and_b32_e32 v132, 0xffffff80, v134
	v_sub_u32_e32 v106, v106, v234
	v_sub_u32_e32 v132, v132, v234
	v_add_u32_e32 v115, 0x6d, v106
	v_and_b32_e32 v106, 0xffffff80, v109
	v_add_u32_e32 v163, 0x4d, v132
	v_and_b32_e32 v132, 0xffffff80, v135
	v_sub_u32_e32 v106, v106, v234
	v_sub_u32_e32 v132, v132, v234
	v_add_u32_e32 v116, 0x6c, v106
	s_waitcnt lgkmcnt(0)
	v_and_b32_e32 v106, 0xffffff80, v110
	v_add_u32_e32 v164, 0x4c, v132
	v_and_b32_e32 v132, 0xffffff80, v136
	v_sub_u32_e32 v106, v106, v234
	v_sub_u32_e32 v132, v132, v234
	v_add_u32_e32 v117, 0x6b, v106
	v_and_b32_e32 v106, 0xffffff80, v111
	v_add_u32_e32 v165, 0x4b, v132
	v_and_b32_e32 v132, 0xffffff80, v137
	v_sub_u32_e32 v106, v106, v234
	v_sub_u32_e32 v132, v132, v234
	v_add_u32_e32 v118, 0x6a, v106
	v_and_b32_e32 v106, 0xffffff80, v112
	v_add_u32_e32 v166, 0x4a, v132
	v_and_b32_e32 v132, 0xffffff80, v138
	v_sub_u32_e32 v106, v106, v234
	v_sub_u32_e32 v132, v132, v234
	v_add_u32_e32 v119, 0x69, v106
	ds_read_b128 v[106:109], v235 offset:96
	v_and_b32_e32 v110, 0xffffff80, v113
	v_add_u32_e32 v167, 0x49, v132
	ds_read_b128 v[132:135], v235 offset:224
	v_and_b32_e32 v136, 0xffffff80, v139
	v_sub_u32_e32 v110, v110, v234
	v_sub_u32_e32 v136, v136, v234
	v_add_u32_e32 v120, 0x68, v110
	ds_read_b128 v[110:113], v235 offset:112
	v_add_u32_e32 v168, 0x48, v136
	ds_read_b128 v[136:139], v235 offset:240
	v_sub_u32_e32 v105, v105, v234
	v_add_u32_e32 v105, 0x6f, v105
	s_waitcnt lgkmcnt(3)
	v_and_b32_e32 v106, 0xffffff80, v106
	v_and_b32_e32 v107, 0xffffff80, v107
	v_max_f32_e32 v114, v114, v114
	v_max_f32_e32 v105, v105, v105
	s_waitcnt lgkmcnt(2)
; DI void phase_peer_query(const Params& p, char* lds) {
;     ...
;           for (int gq = 0; gq < 4; ++gq) {
; #pragma unroll
;             for (int e4 = 0; e4 < 4; ++e4) {
;               const float4 s4 = *(const float4*)(srow + 16 * gq + 4 * e4);
;               const float sv[4] = {s4.x, s4.y, s4.z, s4.w};
; #pragma unroll
;               for (int u = 0; u < 4; ++u)
;                 kq[gq][4 * e4 + u] = __uint_as_float((__float_as_uint(sv[u]) & 0xFFFFFF80u) | (unsigned)(127 - (half * 64 + 16 * gq + 4 * e4 + u)));
;             }
; #pragma unroll
;             for (int kk2 = 2; kk2 <= 16; kk2 <<= 1)
; #pragma unroll
;               for (int j = kk2 >> 1; j > 0; j >>= 1)
; #pragma unroll
;                 for (int i = 0; i < 16; ++i) {
;                   const int l = i ^ j;
;                   if (l > i) {
;                     const float hi = fmaxf(kq[gq][i], kq[gq][l]), lo = fminf(kq[gq][i], kq[gq][l]);
;                     const bool desc = (i & kk2) == 0;
;                     kq[gq][i] = desc ? hi : lo; kq[gq][l] = desc ? lo : hi;
;                   }
;                 }
;           }
	v_and_b32_e32 v132, 0xffffff80, v132
	v_and_b32_e32 v133, 0xffffff80, v133
	v_max_f32_e32 v162, v162, v162
	v_max_f32_e32 v161, v161, v161
	v_sub_u32_e32 v106, v106, v234
	v_sub_u32_e32 v107, v107, v234
	v_and_b32_e32 v108, 0xffffff80, v108
	v_and_b32_e32 v109, 0xffffff80, v109
	v_max_f32_e32 v121, v105, v114
	v_min_f32_e32 v105, v105, v114
	v_max_f32_e32 v114, v116, v116
	v_max_f32_e32 v115, v115, v115
	v_sub_u32_e32 v132, v132, v234
	v_sub_u32_e32 v133, v133, v234
	v_and_b32_e32 v134, 0xffffff80, v134
	v_and_b32_e32 v135, 0xffffff80, v135
	v_max_f32_e32 v169, v161, v162
	v_min_f32_e32 v161, v161, v162
	v_max_f32_e32 v162, v164, v164
	v_max_f32_e32 v163, v163, v163
	v_add_u32_e32 v106, 0x67, v106
	v_add_u32_e32 v107, 0x66, v107
	v_sub_u32_e32 v108, v108, v234
	v_sub_u32_e32 v109, v109, v234
	s_waitcnt lgkmcnt(1)
	v_and_b32_e32 v110, 0xffffff80, v110
	v_and_b32_e32 v111, 0xffffff80, v111
	v_max_f32_e32 v116, v115, v114
	v_min_f32_e32 v114, v115, v114
	v_max_f32_e32 v115, v118, v118
	v_max_f32_e32 v117, v117, v117
	v_add_u32_e32 v132, 0x47, v132
	v_add_u32_e32 v133, 0x46, v133
	v_sub_u32_e32 v134, v134, v234
	v_sub_u32_e32 v135, v135, v234
	s_waitcnt lgkmcnt(0)
	v_and_b32_e32 v136, 0xffffff80, v136
	v_and_b32_e32 v137, 0xffffff80, v137
	v_max_f32_e32 v164, v163, v162
	v_min_f32_e32 v162, v163, v162
	v_max_f32_e32 v163, v166, v166
	v_max_f32_e32 v165, v165, v165
	v_add_u32_e32 v108, 0x65, v108
	v_add_u32_e32 v109, 0x64, v109
	v_sub_u32_e32 v110, v110, v234
	v_sub_u32_e32 v111, v111, v234
	v_and_b32_e32 v112, 0xffffff80, v112
	v_and_b32_e32 v113, 0xffffff80, v113
	v_max_f32_e32 v118, v117, v115
	v_min_f32_e32 v115, v117, v115
	v_max_f32_e32 v117, v120, v120
	v_max_f32_e32 v119, v119, v119
	v_max_f32_e32 v107, v107, v107
	v_max_f32_e32 v106, v106, v106
	v_add_u32_e32 v134, 0x45, v134
	v_add_u32_e32 v135, 0x44, v135
	v_sub_u32_e32 v136, v136, v234
	v_sub_u32_e32 v137, v137, v234
	v_and_b32_e32 v138, 0xffffff80, v138
	v_and_b32_e32 v139, 0xffffff80, v139
	v_max_f32_e32 v166, v165, v163
	v_min_f32_e32 v163, v165, v163
	v_max_f32_e32 v165, v168, v168
	v_max_f32_e32 v167, v167, v167
	v_max_f32_e32 v133, v133, v133
	v_max_f32_e32 v132, v132, v132
	v_add_u32_e32 v110, 0x63, v110
	v_add_u32_e32 v111, 0x62, v111
	v_sub_u32_e32 v112, v112, v234
	v_sub_u32_e32 v113, v113, v234
	v_max_f32_e32 v120, v119, v117
	v_min_f32_e32 v117, v119, v117
	v_max_f32_e32 v119, v106, v107
	v_min_f32_e32 v106, v106, v107
	v_max_f32_e32 v107, v109, v109
	v_max_f32_e32 v108, v108, v108
	v_add_u32_e32 v136, 0x43, v136
	v_add_u32_e32 v137, 0x42, v137
	v_sub_u32_e32 v138, v138, v234
	v_sub_u32_e32 v139, v139, v234
	v_max_f32_e32 v168, v167, v165
	v_min_f32_e32 v165, v167, v165
	v_max_f32_e32 v167, v132, v133
	v_min_f32_e32 v132, v132, v133
	v_max_f32_e32 v133, v135, v135
	v_max_f32_e32 v134, v134, v134
	v_add_u32_e32 v112, 0x61, v112
	v_add_u32_e32 v113, 0x60, v113
	v_max_f32_e32 v109, v108, v107
	v_min_f32_e32 v107, v108, v107
	v_max_f32_e32 v108, v111, v111
	v_max_f32_e32 v110, v110, v110
	v_add_u32_e32 v138, 0x41, v138
	v_add_u32_e32 v139, 64, v139
	v_max_f32_e32 v135, v134, v133
	v_min_f32_e32 v133, v134, v133
	v_max_f32_e32 v134, v137, v137
	v_max_f32_e32 v136, v136, v136
	v_max_f32_e32 v111, v110, v108
	v_min_f32_e32 v108, v110, v108
	v_max_f32_e32 v110, v113, v113
	v_max_f32_e32 v112, v112, v112
	v_max_f32_e32 v137, v136, v134
	v_min_f32_e32 v134, v136, v134
	v_max_f32_e32 v136, v139, v139
	v_max_f32_e32 v138, v138, v138
	v_max_f32_e32 v113, v112, v110
	v_min_f32_e32 v110, v112, v110
	v_max_f32_e32 v139, v138, v136
	v_min_f32_e32 v136, v138, v136
	v_max_f32_e32 v112, v121, v114
	v_min_f32_e32 v114, v121, v114
	v_max_f32_e32 v121, v105, v116
	v_min_f32_e32 v105, v105, v116
	v_max_f32_e32 v116, v118, v117
	v_min_f32_e32 v117, v118, v117
	v_max_f32_e32 v118, v115, v120
	v_min_f32_e32 v115, v115, v120
	v_max_f32_e32 v120, v119, v107
	v_min_f32_e32 v107, v119, v107
	v_max_f32_e32 v119, v106, v109
	v_min_f32_e32 v106, v106, v109
	v_max_f32_e32 v109, v111, v110
	v_min_f32_e32 v110, v111, v110
	v_max_f32_e32 v111, v108, v113
	v_min_f32_e32 v108, v108, v113
	v_max_f32_e32 v138, v169, v162
	v_min_f32_e32 v162, v169, v162
	v_max_f32_e32 v169, v161, v164
	v_min_f32_e32 v161, v161, v164
	v_max_f32_e32 v164, v166, v165
	v_min_f32_e32 v165, v166, v165
	v_max_f32_e32 v166, v163, v168
	v_min_f32_e32 v163, v163, v168
	v_max_f32_e32 v168, v167, v133
	v_min_f32_e32 v133, v167, v133
	v_max_f32_e32 v167, v132, v135
	v_min_f32_e32 v132, v132, v135
	v_max_f32_e32 v135, v137, v136
	v_min_f32_e32 v136, v137, v136
	v_max_f32_e32 v137, v134, v139
	v_min_f32_e32 v134, v134, v139
	v_max_f32_e32 v113, v112, v121
	v_min_f32_e32 v112, v112, v121
	v_max_f32_e32 v121, v114, v105
	v_min_f32_e32 v105, v114, v105
	v_max_f32_e32 v114, v117, v115
	v_min_f32_e32 v115, v117, v115
	v_max_f32_e32 v117, v116, v118
	v_min_f32_e32 v116, v116, v118
	v_max_f32_e32 v118, v120, v119
	v_min_f32_e32 v119, v120, v119
	v_max_f32_e32 v120, v107, v106
	v_min_f32_e32 v106, v107, v106
	v_max_f32_e32 v107, v110, v108
	v_min_f32_e32 v108, v110, v108
	v_max_f32_e32 v110, v109, v111
	v_min_f32_e32 v109, v109, v111
	v_max_f32_e32 v139, v138, v169
	v_min_f32_e32 v138, v138, v169
	v_max_f32_e32 v169, v162, v161
	v_min_f32_e32 v161, v162, v161
	v_max_f32_e32 v162, v165, v163
	v_min_f32_e32 v163, v165, v163
	v_max_f32_e32 v165, v164, v166
	v_min_f32_e32 v164, v164, v166
	v_max_f32_e32 v166, v168, v167
	v_min_f32_e32 v167, v168, v167
	v_max_f32_e32 v168, v133, v132
	v_min_f32_e32 v132, v133, v132
	v_max_f32_e32 v133, v136, v134
	v_min_f32_e32 v134, v136, v134
	v_max_f32_e32 v136, v135, v137
	v_min_f32_e32 v135, v135, v137
; DI void phase_peer_query(const Params& p, char* lds) {
;     ...
;             for (int kk2 = 2; kk2 <= 16; kk2 <<= 1)
; #pragma unroll
;               for (int j = kk2 >> 1; j > 0; j >>= 1)
; #pragma unroll
;                 for (int i = 0; i < 16; ++i) {
;                   const int l = i ^ j;
;                   if (l > i) {
;                     const float hi = fmaxf(kq[gq][i], kq[gq][l]), lo = fminf(kq[gq][i], kq[gq][l]);
;                     const bool desc = (i & kk2) == 0;
;                     kq[gq][i] = desc ? hi : lo; kq[gq][l] = desc ? lo : hi;
;                   }
;                 }
;           }
; #pragma unroll
;           for (int pr = 0; pr < 2; ++pr) {
; #pragma unroll
;             for (int i = 0; i < 16; ++i) kq[2 * pr][i] = fmaxf(kq[2 * pr][i], kq[2 * pr + 1][15 - i]);
; #pragma unroll
;             for (int d = 8; d >= 1; d >>= 1)
; #pragma unroll
;               for (int i = 0; i < 16; ++i)
;                 if ((i & d) == 0) { const float hi = fmaxf(kq[2 * pr][i], kq[2 * pr][i + d]), lo = fminf(kq[2 * pr][i], kq[2 * pr][i + d]); kq[2 * pr][i] = hi; kq[2 * pr][i + d] = lo; }
;           }
	v_max_f32_e32 v111, v113, v115
	v_min_f32_e32 v113, v113, v115
	v_max_f32_e32 v115, v112, v114
	v_min_f32_e32 v112, v112, v114
	v_max_f32_e32 v114, v121, v116
	v_min_f32_e32 v116, v121, v116
	v_max_f32_e32 v121, v105, v117
	v_min_f32_e32 v105, v105, v117
	v_max_f32_e32 v117, v118, v108
	v_min_f32_e32 v108, v118, v108
	v_max_f32_e32 v118, v119, v107
	v_min_f32_e32 v107, v119, v107
	v_max_f32_e32 v119, v120, v109
	v_min_f32_e32 v109, v120, v109
	v_max_f32_e32 v120, v106, v110
	v_min_f32_e32 v106, v106, v110
	v_max_f32_e32 v137, v139, v163
	v_min_f32_e32 v139, v139, v163
	v_max_f32_e32 v163, v138, v162
	v_min_f32_e32 v138, v138, v162
	v_max_f32_e32 v162, v169, v164
	v_min_f32_e32 v164, v169, v164
	v_max_f32_e32 v169, v161, v165
	v_min_f32_e32 v161, v161, v165
	v_max_f32_e32 v165, v166, v134
	v_min_f32_e32 v134, v166, v134
	v_max_f32_e32 v166, v167, v133
	v_min_f32_e32 v133, v167, v133
	v_max_f32_e32 v167, v168, v135
	v_min_f32_e32 v135, v168, v135
	v_max_f32_e32 v168, v132, v136
	v_min_f32_e32 v132, v132, v136
	v_max_f32_e32 v110, v111, v114
	v_min_f32_e32 v111, v111, v114
	v_max_f32_e32 v114, v115, v121
	v_min_f32_e32 v115, v115, v121
	v_max_f32_e32 v121, v113, v116
	v_min_f32_e32 v113, v113, v116
	v_max_f32_e32 v116, v112, v105
	v_min_f32_e32 v105, v112, v105
	v_max_f32_e32 v112, v108, v109
	v_min_f32_e32 v108, v108, v109
	v_max_f32_e32 v109, v107, v106
	v_min_f32_e32 v106, v107, v106
	v_max_f32_e32 v107, v117, v119
	v_min_f32_e32 v117, v117, v119
	v_max_f32_e32 v119, v118, v120
	v_min_f32_e32 v118, v118, v120
	v_max_f32_e32 v136, v137, v162
	v_min_f32_e32 v137, v137, v162
	v_max_f32_e32 v162, v163, v169
	v_min_f32_e32 v163, v163, v169
	v_max_f32_e32 v169, v139, v164
	v_min_f32_e32 v139, v139, v164
	v_max_f32_e32 v164, v138, v161
	v_min_f32_e32 v138, v138, v161
	v_max_f32_e32 v161, v134, v135
	v_min_f32_e32 v134, v134, v135
	v_max_f32_e32 v135, v133, v132
	v_min_f32_e32 v132, v133, v132
	v_max_f32_e32 v133, v165, v167
	v_min_f32_e32 v165, v165, v167
	v_max_f32_e32 v167, v166, v168
	v_min_f32_e32 v166, v166, v168
	v_max_f32_e32 v120, v110, v114
	v_min_f32_e32 v110, v110, v114
	v_max_f32_e32 v114, v111, v115
	v_min_f32_e32 v111, v111, v115
	v_max_f32_e32 v115, v121, v116
	v_min_f32_e32 v116, v121, v116
	v_max_f32_e32 v121, v113, v105
	v_min_f32_e32 v105, v113, v105
	v_max_f32_e32 v113, v108, v106
	v_min_f32_e32 v106, v108, v106
	v_max_f32_e32 v108, v112, v109
	v_min_f32_e32 v109, v112, v109
	v_max_f32_e32 v112, v117, v118
	v_min_f32_e32 v117, v117, v118
	v_max_f32_e32 v118, v107, v119
	v_min_f32_e32 v107, v107, v119
	v_max_f32_e32 v168, v136, v162
	v_min_f32_e32 v136, v136, v162
	v_max_f32_e32 v162, v137, v163
	v_min_f32_e32 v137, v137, v163
	v_max_f32_e32 v163, v169, v164
	v_min_f32_e32 v164, v169, v164
	v_max_f32_e32 v169, v139, v138
	v_min_f32_e32 v138, v139, v138
	v_max_f32_e32 v139, v134, v132
	v_min_f32_e32 v132, v134, v132
	v_max_f32_e32 v134, v161, v135
	v_min_f32_e32 v135, v161, v135
	v_max_f32_e32 v161, v165, v166
	v_min_f32_e32 v165, v165, v166
	v_max_f32_e32 v166, v133, v167
	v_min_f32_e32 v133, v133, v167
	v_max_f32_e32 v119, v120, v106
	v_min_f32_e32 v106, v120, v106
	v_max_f32_e32 v120, v110, v113
	v_min_f32_e32 v110, v110, v113
	v_max_f32_e32 v113, v114, v109
	v_min_f32_e32 v109, v114, v109
	v_max_f32_e32 v114, v111, v108
	v_min_f32_e32 v108, v111, v108
	v_max_f32_e32 v111, v115, v117
	v_min_f32_e32 v115, v115, v117
	v_max_f32_e32 v117, v116, v112
	v_min_f32_e32 v112, v116, v112
	v_max_f32_e32 v116, v121, v107
	v_min_f32_e32 v107, v121, v107
	v_max_f32_e32 v121, v105, v118
	v_min_f32_e32 v105, v105, v118
	v_max_f32_e32 v167, v168, v132
	v_min_f32_e32 v132, v168, v132
	v_max_f32_e32 v168, v136, v139
	v_min_f32_e32 v136, v136, v139
	v_max_f32_e32 v139, v162, v135
	v_min_f32_e32 v135, v162, v135
	v_max_f32_e32 v162, v137, v134
	v_min_f32_e32 v134, v137, v134
	v_max_f32_e32 v137, v163, v165
	v_min_f32_e32 v163, v163, v165
	v_max_f32_e32 v165, v164, v161
	v_min_f32_e32 v161, v164, v161
	v_max_f32_e32 v164, v169, v133
	v_min_f32_e32 v133, v169, v133
	v_max_f32_e32 v169, v138, v166
	v_min_f32_e32 v138, v138, v166
	v_max_f32_e32 v118, v119, v111
	v_min_f32_e32 v111, v119, v111
	v_max_f32_e32 v119, v120, v117
	v_min_f32_e32 v117, v120, v117
	v_max_f32_e32 v120, v113, v116
	v_min_f32_e32 v113, v113, v116
	v_max_f32_e32 v116, v114, v121
	v_min_f32_e32 v114, v114, v121
	v_max_f32_e32 v121, v106, v115
	v_min_f32_e32 v115, v106, v115
	v_max_f32_e32 v122, v110, v112
	v_min_f32_e32 v124, v110, v112
	v_max_f32_e32 v123, v109, v107
	v_min_f32_e32 v125, v109, v107
	v_max_f32_e32 v126, v108, v105
	v_min_f32_e32 v127, v108, v105
	v_max_f32_e32 v166, v167, v137
	v_min_f32_e32 v137, v167, v137
	v_max_f32_e32 v167, v168, v165
	v_min_f32_e32 v165, v168, v165
	v_max_f32_e32 v168, v139, v164
	v_min_f32_e32 v139, v139, v164
	v_max_f32_e32 v164, v162, v169
	v_min_f32_e32 v162, v162, v169
	v_max_f32_e32 v169, v132, v163
	v_min_f32_e32 v132, v132, v163
	v_max_f32_e32 v163, v136, v161
	v_min_f32_e32 v136, v136, v161
	v_max_f32_e32 v161, v135, v133
	v_min_f32_e32 v133, v135, v133
	v_max_f32_e32 v135, v134, v138
	v_min_f32_e32 v134, v134, v138
	v_max_f32_e32 v83, v97, v103
	v_min_f32_e32 v87, v97, v103
	v_max_f32_e32 v86, v98, v100
	v_min_f32_e32 v85, v98, v100
	v_max_f32_e32 v89, v99, v101
	v_min_f32_e32 v88, v99, v101
	v_max_f32_e32 v105, v118, v120
	v_min_f32_e32 v107, v118, v120
	v_max_f32_e32 v106, v119, v116
	v_min_f32_e32 v108, v119, v116
	v_max_f32_e32 v109, v111, v113
	v_min_f32_e32 v111, v111, v113
	v_max_f32_e32 v110, v117, v114
	v_min_f32_e32 v112, v117, v114
	v_max_f32_e32 v113, v121, v123
	v_min_f32_e32 v116, v121, v123
	v_max_f32_e32 v114, v122, v126
; DI void phase_peer_query(const Params& p, char* lds) {
;     ...
; #pragma unroll
;           for (int pr = 0; pr < 2; ++pr) {
; #pragma unroll
;             for (int i = 0; i < 16; ++i) kq[2 * pr][i] = fmaxf(kq[2 * pr][i], kq[2 * pr + 1][15 - i]);
; #pragma unroll
;             for (int d = 8; d >= 1; d >>= 1)
; #pragma unroll
;               for (int i = 0; i < 16; ++i)
;                 if ((i & d) == 0) { const float hi = fmaxf(kq[2 * pr][i], kq[2 * pr][i + d]), lo = fminf(kq[2 * pr][i], kq[2 * pr][i + d]); kq[2 * pr][i] = hi; kq[2 * pr][i + d] = lo; }
;           }
; #pragma unroll
;           for (int i = 0; i < 16; ++i) v[i] = fmaxf(kq[0][i], kq[2][15 - i]);
; #pragma unroll
;           for (int d = 8; d >= 1; d >>= 1)
; #pragma unroll
;             for (int i = 0; i < 16; ++i)
;               if ((i & d) == 0) { const float hi = fmaxf(v[i], v[i + d]), lo = fminf(v[i], v[i + d]); v[i] = hi; v[i + d] = lo; }
	v_min_f32_e32 v118, v122, v126
	v_max_f32_e32 v120, v115, v125
	v_min_f32_e32 v123, v115, v125
	v_max_f32_e32 v122, v124, v127
	v_min_f32_e32 v124, v124, v127
	v_max_f32_e32 v138, v166, v168
	v_min_f32_e32 v166, v166, v168
	v_max_f32_e32 v168, v167, v164
	v_min_f32_e32 v164, v167, v164
	v_max_f32_e32 v167, v137, v139
	v_min_f32_e32 v137, v137, v139
	v_max_f32_e32 v139, v165, v162
	v_min_f32_e32 v162, v165, v162
	v_max_f32_e32 v165, v169, v161
	v_min_f32_e32 v161, v169, v161
	v_max_f32_e32 v169, v163, v135
	v_min_f32_e32 v135, v163, v135
	v_max_f32_e32 v163, v132, v133
	v_min_f32_e32 v132, v132, v133
	v_max_f32_e32 v133, v136, v134
	v_min_f32_e32 v134, v136, v134
	v_min_f32_e32 v101, v65, v90
	v_min_f32_e32 v100, v91, v94
	v_min_f32_e32 v99, v93, v96
	v_min_f32_e32 v97, v92, v95
	v_min_f32_e32 v98, v82, v83
	v_min_f32_e32 v104, v84, v87
	v_min_f32_e32 v103, v86, v89
	v_min_f32_e32 v102, v85, v88
	v_min_f32_e32 v115, v105, v106
	v_min_f32_e32 v119, v107, v108
	v_min_f32_e32 v121, v109, v110
	v_min_f32_e32 v117, v111, v112
	v_min_f32_e32 v125, v113, v114
	v_min_f32_e32 v127, v116, v118
	v_min_f32_e32 v128, v120, v122
	v_min_f32_e32 v126, v123, v124
	v_min_f32_e32 v153, v129, v130
	v_min_f32_e32 v154, v142, v140
	v_min_f32_e32 v155, v143, v147
	v_min_f32_e32 v156, v144, v141
	v_min_f32_e32 v157, v148, v149
	v_min_f32_e32 v158, v145, v146
	v_min_f32_e32 v159, v150, v151
	v_min_f32_e32 v160, v131, v152
	v_min_f32_e32 v136, v138, v168
	v_min_f32_e32 v170, v166, v164
	v_min_f32_e32 v171, v167, v139
	v_min_f32_e32 v172, v137, v162
	v_min_f32_e32 v173, v165, v169
	v_min_f32_e32 v174, v161, v135
	v_min_f32_e32 v175, v163, v133
	v_min_f32_e32 v176, v132, v134
	v_max3_f32 v101, v101, v123, v124
	v_max3_f32 v91, v91, v94, v128
	v_max3_f32 v94, v100, v120, v122
	v_max3_f32 v93, v93, v96, v127
	v_max3_f32 v96, v99, v116, v118
	v_max3_f32 v92, v92, v95, v125
	v_max3_f32 v95, v97, v113, v114
	v_max3_f32 v97, v98, v111, v112
	v_max3_f32 v84, v84, v87, v121
	v_max3_f32 v87, v104, v109, v110
	v_max3_f32 v86, v86, v89, v119
	v_max3_f32 v89, v103, v107, v108
	v_max3_f32 v85, v85, v88, v115
	v_max3_f32 v88, v102, v105, v106
	v_max3_f32 v82, v82, v83, v117
	v_max3_f32 v65, v65, v90, v126
	v_max3_f32 v105, v153, v132, v134
	v_max3_f32 v106, v142, v140, v175
	v_max3_f32 v107, v154, v163, v133
	v_max3_f32 v108, v143, v147, v174
	v_max3_f32 v109, v155, v161, v135
	v_max3_f32 v110, v144, v141, v173
	v_max3_f32 v111, v156, v165, v169
	v_max3_f32 v112, v157, v137, v162
	v_max3_f32 v113, v145, v146, v171
	v_max3_f32 v114, v158, v167, v139
	v_max3_f32 v115, v150, v151, v170
	v_max3_f32 v116, v159, v166, v164
	v_max3_f32 v117, v131, v152, v136
	v_max3_f32 v118, v160, v138, v168
	v_max3_f32 v119, v148, v149, v172
	v_max3_f32 v120, v129, v130, v176
	v_max_f32_e32 v83, v65, v82
	v_min_f32_e32 v65, v65, v82
	v_max_f32_e32 v82, v101, v97
	v_min_f32_e32 v90, v101, v97
	v_max_f32_e32 v97, v91, v84
	v_min_f32_e32 v84, v91, v84
	v_max_f32_e32 v91, v94, v87
	v_min_f32_e32 v87, v94, v87
	v_max_f32_e32 v94, v93, v86
	v_min_f32_e32 v86, v93, v86
	v_max_f32_e32 v93, v96, v89
	v_min_f32_e32 v89, v96, v89
	v_max_f32_e32 v96, v92, v85
	v_min_f32_e32 v85, v92, v85
	v_max_f32_e32 v92, v95, v88
	v_min_f32_e32 v88, v95, v88
	v_max_f32_e32 v121, v120, v119
	v_min_f32_e32 v119, v120, v119
	v_max_f32_e32 v120, v105, v112
	v_min_f32_e32 v105, v105, v112
	v_max_f32_e32 v112, v106, v113
	v_min_f32_e32 v106, v106, v113
	v_max_f32_e32 v113, v107, v114
	v_min_f32_e32 v107, v107, v114
	v_max_f32_e32 v114, v108, v115
	v_min_f32_e32 v108, v108, v115
	v_max_f32_e32 v115, v109, v116
	v_min_f32_e32 v109, v109, v116
	v_max_f32_e32 v116, v110, v117
	v_min_f32_e32 v110, v110, v117
	v_max_f32_e32 v117, v111, v118
	v_min_f32_e32 v111, v111, v118
	v_max_f32_e32 v95, v83, v94
	v_min_f32_e32 v83, v83, v94
	v_max_f32_e32 v94, v82, v93
	v_min_f32_e32 v82, v82, v93
	v_max_f32_e32 v93, v97, v96
	v_min_f32_e32 v96, v97, v96
	v_max_f32_e32 v97, v91, v92
	v_min_f32_e32 v91, v91, v92
	v_max_f32_e32 v92, v65, v86
	v_min_f32_e32 v65, v65, v86
	v_max_f32_e32 v86, v90, v89
	v_min_f32_e32 v89, v90, v89
	v_max_f32_e32 v90, v84, v85
	v_min_f32_e32 v84, v84, v85
	v_max_f32_e32 v85, v87, v88
	v_min_f32_e32 v87, v87, v88
	v_max_f32_e32 v118, v121, v114
	v_min_f32_e32 v114, v121, v114
	v_max_f32_e32 v121, v120, v115
	v_min_f32_e32 v115, v120, v115
	v_max_f32_e32 v120, v112, v116
	v_min_f32_e32 v112, v112, v116
	v_max_f32_e32 v116, v113, v117
	v_min_f32_e32 v113, v113, v117
	v_max_f32_e32 v117, v119, v108
	v_min_f32_e32 v108, v119, v108
	v_max_f32_e32 v119, v105, v109
	v_min_f32_e32 v105, v105, v109
	v_max_f32_e32 v109, v106, v110
	v_min_f32_e32 v106, v106, v110
	v_max_f32_e32 v110, v107, v111
	v_min_f32_e32 v107, v107, v111
	v_max_f32_e32 v88, v95, v93
	v_min_f32_e32 v93, v95, v93
	v_max_f32_e32 v95, v94, v97
	v_min_f32_e32 v94, v94, v97
	v_max_f32_e32 v97, v83, v96
	v_min_f32_e32 v83, v83, v96
	v_max_f32_e32 v96, v82, v91
	v_min_f32_e32 v82, v82, v91
	v_max_f32_e32 v91, v92, v90
	v_min_f32_e32 v90, v92, v90
	v_max_f32_e32 v92, v86, v85
	v_min_f32_e32 v85, v86, v85
	v_max_f32_e32 v86, v65, v84
	v_min_f32_e32 v65, v65, v84
	v_max_f32_e32 v84, v89, v87
	v_min_f32_e32 v87, v89, v87
	v_max_f32_e32 v111, v118, v120
	v_min_f32_e32 v118, v118, v120
	v_max_f32_e32 v120, v121, v116
	v_min_f32_e32 v116, v121, v116
	v_max_f32_e32 v121, v114, v112
	v_min_f32_e32 v112, v114, v112
	v_max_f32_e32 v114, v115, v113
	v_min_f32_e32 v113, v115, v113
	v_max_f32_e32 v115, v117, v109
	v_min_f32_e32 v109, v117, v109
	v_max_f32_e32 v117, v119, v110
	v_min_f32_e32 v110, v119, v110
	v_max_f32_e32 v119, v108, v106
	v_min_f32_e32 v106, v108, v106
; DI void phase_peer_query(const Params& p, char* lds) {
;     ...
;           for (int i = 0; i < 16; ++i) v[i] = fmaxf(kq[0][i], kq[2][15 - i]);
; #pragma unroll
;           for (int d = 8; d >= 1; d >>= 1)
; #pragma unroll
;             for (int i = 0; i < 16; ++i)
;               if ((i & d) == 0) { const float hi = fmaxf(v[i], v[i + d]), lo = fminf(v[i], v[i + d]); v[i] = hi; v[i + d] = lo; }
;         }
;         float c[16];
; #pragma unroll
;         for (int i = 0; i < 16; ++i) c[i] = __shfl_xor(v[15 - i], 1);
; #pragma unroll
;         for (int i = 0; i < 16; ++i) c[i] = fmaxf(c[i], v[i]);
; #pragma unroll
;         for (int d = 8; d >= 1; d >>= 1)
; #pragma unroll
;           for (int i = 0; i < 16; ++i)
;             if ((i & d) == 0) { const float hi = fmaxf(c[i], c[i + d]), lo = fminf(c[i], c[i + d]); c[i] = hi; c[i + d] = lo; }
;         if (half == 0) {
	v_max_f32_e32 v108, v105, v107
	v_min_f32_e32 v105, v105, v107
	v_min_f32_e32 v89, v88, v95
	v_min_f32_e32 v98, v93, v94
	v_min_f32_e32 v99, v97, v96
	v_min_f32_e32 v100, v83, v82
	v_min_f32_e32 v101, v91, v92
	v_min_f32_e32 v102, v90, v85
	v_min_f32_e32 v103, v86, v84
	v_min_f32_e32 v104, v65, v87
	v_min_f32_e32 v107, v111, v120
	v_min_f32_e32 v122, v118, v116
	v_min_f32_e32 v123, v121, v114
	v_min_f32_e32 v124, v112, v113
	v_min_f32_e32 v125, v115, v117
	v_min_f32_e32 v126, v109, v110
	v_min_f32_e32 v127, v119, v108
	v_min_f32_e32 v128, v106, v105
	v_max3_f32 v89, v89, v106, v105
	v_max3_f32 v93, v93, v94, v127
	v_max3_f32 v94, v98, v119, v108
	v_max3_f32 v96, v97, v96, v126
	v_max3_f32 v97, v99, v109, v110
	v_max3_f32 v82, v83, v82, v125
	v_max3_f32 v83, v100, v115, v117
	v_max3_f32 v98, v101, v112, v113
	v_max3_f32 v85, v90, v85, v123
	v_max3_f32 v90, v102, v121, v114
	v_max3_f32 v84, v86, v84, v122
	v_max3_f32 v86, v103, v118, v116
	v_max3_f32 v65, v65, v87, v107
	v_max3_f32 v87, v104, v111, v120
	v_max3_f32 v91, v91, v92, v124
	v_max3_f32 v88, v88, v95, v128
	v_max_f32_e32 v92, v88, v91
	v_min_f32_e32 v88, v88, v91
	v_max_f32_e32 v91, v89, v98
	v_min_f32_e32 v89, v89, v98
	v_max_f32_e32 v95, v93, v85
	v_min_f32_e32 v85, v93, v85
	v_max_f32_e32 v93, v94, v90
	v_min_f32_e32 v90, v94, v90
	v_max_f32_e32 v94, v96, v84
	v_min_f32_e32 v84, v96, v84
	v_max_f32_e32 v96, v97, v86
	v_min_f32_e32 v86, v97, v86
	v_max_f32_e32 v97, v82, v65
	v_min_f32_e32 v65, v82, v65
	v_max_f32_e32 v82, v83, v87
	v_min_f32_e32 v83, v83, v87
	v_max_f32_e32 v87, v92, v94
	v_min_f32_e32 v92, v92, v94
	v_max_f32_e32 v94, v91, v96
	v_min_f32_e32 v91, v91, v96
	v_max_f32_e32 v96, v95, v97
	v_min_f32_e32 v95, v95, v97
	v_max_f32_e32 v97, v93, v82
	v_min_f32_e32 v82, v93, v82
	v_max_f32_e32 v93, v88, v84
	v_min_f32_e32 v84, v88, v84
	v_max_f32_e32 v88, v89, v86
	v_min_f32_e32 v86, v89, v86
	v_max_f32_e32 v89, v85, v65
	v_min_f32_e32 v65, v85, v65
	v_max_f32_e32 v85, v90, v83
	v_min_f32_e32 v83, v90, v83
	v_max_f32_e32 v90, v87, v96
	v_min_f32_e32 v87, v87, v96
	v_max_f32_e32 v96, v94, v97
	v_min_f32_e32 v94, v94, v97
	v_max_f32_e32 v98, v92, v95
	v_min_f32_e32 v92, v92, v95
	v_max_f32_e32 v95, v91, v82
	v_min_f32_e32 v82, v91, v82
	v_max_f32_e32 v91, v93, v89
	v_min_f32_e32 v89, v93, v89
	v_max_f32_e32 v93, v88, v85
	v_min_f32_e32 v85, v88, v85
	v_max_f32_e32 v99, v84, v65
	v_min_f32_e32 v65, v84, v65
	v_max_f32_e32 v84, v86, v83
	v_min_f32_e32 v100, v86, v83
	v_max_f32_e32 v104, v90, v96
	v_min_f32_e32 v88, v90, v96
	v_max_f32_e32 v97, v87, v94
	v_min_f32_e32 v83, v87, v94
	v_max_f32_e32 v102, v98, v95
	v_min_f32_e32 v86, v98, v95
	v_max_f32_e32 v95, v92, v82
	v_min_f32_e32 v82, v92, v82
	v_max_f32_e32 v108, v91, v93
	v_min_f32_e32 v92, v91, v93
	v_max_f32_e32 v101, v89, v85
	v_min_f32_e32 v85, v89, v85
	v_max_f32_e32 v105, v99, v84
	v_min_f32_e32 v89, v99, v84
	v_max_f32_e32 v99, v65, v100
	v_min_f32_e32 v84, v65, v100
	ds_bpermute_b32 v111, v218, v84
	ds_bpermute_b32 v96, v218, v99
	ds_bpermute_b32 v106, v218, v89
	ds_bpermute_b32 v90, v218, v105
	ds_bpermute_b32 v110, v218, v85
	ds_bpermute_b32 v94, v218, v101
	ds_bpermute_b32 v103, v218, v92
	ds_bpermute_b32 v87, v218, v108
	ds_bpermute_b32 v113, v218, v82
	ds_bpermute_b32 v100, v218, v95
	ds_bpermute_b32 v109, v218, v86
	ds_bpermute_b32 v93, v218, v102
	ds_bpermute_b32 v112, v218, v83
	ds_bpermute_b32 v98, v218, v97
	ds_bpermute_b32 v107, v218, v88
	ds_bpermute_b32 v91, v218, v104
	v_ashrrev_i32_e32 v65, 31, v64
	v_lshlrev_b64 v[64:65], 10, v[64:65]
	v_lshl_add_u64 v[64:65], s[14:15], 0, v[64:65]
	s_and_saveexec_b64 s[16:17], s[4:5]
	s_cbranch_execz .LBB0_1126
; DI void phase_peer_query(const Params& p, char* lds) {
;     ...
;         for (int i = 0; i < 16; ++i) c[i] = __shfl_xor(v[15 - i], 1);
; #pragma unroll
;         for (int i = 0; i < 16; ++i) c[i] = fmaxf(c[i], v[i]);
; #pragma unroll
;         for (int d = 8; d >= 1; d >>= 1)
; #pragma unroll
;           for (int i = 0; i < 16; ++i)
;             if ((i & d) == 0) { const float hi = fmaxf(c[i], c[i + d]), lo = fminf(c[i], c[i + d]); c[i] = hi; c[i + d] = lo; }
;         if (half == 0) {
;           float* tv = TOPV + (size_t)(m0 + row) * 256 + hp * 16;
; #pragma unroll
;           for (int i = 0; i < 4; ++i) *(float4*)(tv + 4 * i) = make_float4(c[4 * i], c[4 * i + 1], c[4 * i + 2], c[4 * i + 3]);
;         }
	v_max_f32_e32 v83, v83, v83
	s_waitcnt lgkmcnt(12)
	v_max_f32_e32 v90, v90, v90
	v_max_f32_e32 v90, v90, v83
	v_max_f32_e32 v83, v85, v85
	s_waitcnt lgkmcnt(4)
	v_max_f32_e32 v85, v93, v93
	v_max_f32_e32 v104, v104, v104
	v_max_f32_e32 v111, v111, v111
	v_max_f32_e32 v102, v102, v102
	v_max_f32_e32 v110, v110, v110
	v_max_f32_e32 v97, v97, v97
	v_max_f32_e32 v106, v106, v106
	v_max_f32_e32 v95, v95, v95
	v_max_f32_e32 v103, v103, v103
	v_max_f32_e32 v88, v88, v88
	v_max_f32_e32 v96, v96, v96
	v_max_f32_e32 v86, v86, v86
	v_max_f32_e32 v94, v94, v94
	v_max_f32_e32 v93, v85, v83
	v_max_f32_e32 v82, v82, v82
	v_max_f32_e32 v83, v87, v87
	v_max_f32_e32 v104, v111, v104
	v_max_f32_e32 v108, v108, v108
	v_max_f32_e32 v111, v113, v113
	v_max_f32_e32 v102, v110, v102
	v_max_f32_e32 v105, v105, v105
	s_waitcnt lgkmcnt(3)
	v_max_f32_e32 v110, v112, v112
	v_max_f32_e32 v97, v106, v97
	v_max_f32_e32 v101, v101, v101
	v_max_f32_e32 v106, v109, v109
	v_max_f32_e32 v95, v103, v95
	v_max_f32_e32 v99, v99, v99
	s_waitcnt lgkmcnt(1)
	v_max_f32_e32 v103, v107, v107
	v_max_f32_e32 v96, v96, v88
	v_max_f32_e32 v88, v92, v92
	v_max_f32_e32 v92, v100, v100
	v_max_f32_e32 v94, v94, v86
	v_max_f32_e32 v86, v89, v89
	v_max_f32_e32 v89, v98, v98
	v_max_f32_e32 v113, v83, v82
	v_max_f32_e32 v82, v84, v84
	s_waitcnt lgkmcnt(0)
	v_max_f32_e32 v83, v91, v91
	v_max_f32_e32 v108, v111, v108
	v_max_f32_e32 v105, v110, v105
	v_max_f32_e32 v101, v106, v101
	v_max_f32_e32 v99, v103, v99
	v_max_f32_e32 v92, v92, v88
	v_max_f32_e32 v98, v89, v86
	v_max_f32_e32 v91, v83, v82
	v_min_f32_e32 v111, v104, v108
	v_min_f32_e32 v110, v102, v105
	v_min_f32_e32 v106, v97, v101
	v_min_f32_e32 v103, v95, v99
	v_min_f32_e32 v88, v96, v92
	v_min_f32_e32 v86, v94, v98
	v_min_f32_e32 v100, v90, v93
	v_min_f32_e32 v87, v113, v91
	v_min_f32_e32 v112, v111, v110
	v_min_f32_e32 v107, v106, v103
	v_min_f32_e32 v89, v88, v86
	v_min_f32_e32 v82, v100, v87
	v_min_f32_e32 v109, v112, v107
	v_min_f32_e32 v83, v89, v82
	v_max_f32_e32 v107, v112, v107
	v_max_f32_e32 v82, v89, v82
	v_min_f32_e32 v85, v109, v83
	v_max_f32_e32 v84, v109, v83
	v_min_f32_e32 v83, v107, v82
	v_max_f32_e32 v82, v107, v82
	v_max_f32_e32 v107, v111, v110
	v_max_f32_e32 v103, v106, v103
	v_max_f32_e32 v86, v88, v86
	v_max_f32_e32 v87, v100, v87
	v_min_f32_e32 v88, v86, v87
	v_max_f32_e32 v100, v107, v103
	v_max_f32_e32 v86, v86, v87
	v_min_f32_e32 v87, v100, v86
	v_max_f32_e32 v86, v100, v86
	v_max_f32_e32 v100, v104, v108
	v_max_f32_e32 v102, v102, v105
	v_max_f32_e32 v97, v97, v101
	v_max_f32_e32 v95, v95, v99
	v_max_f32_e32 v96, v96, v92
	v_max_f32_e32 v94, v94, v98
	v_max_f32_e32 v104, v90, v93
	v_max_f32_e32 v105, v113, v91
	v_min_f32_e32 v106, v107, v103
	v_min_f32_e32 v103, v100, v102
	v_min_f32_e32 v99, v97, v95
	v_min_f32_e32 v98, v96, v94
	v_min_f32_e32 v90, v104, v105
	v_min_f32_e32 v101, v103, v99
	v_min_f32_e32 v91, v98, v90
	v_max_f32_e32 v99, v103, v99
	v_max_f32_e32 v90, v98, v90
	v_max_f32_e32 v98, v100, v102
	v_max_f32_e32 v95, v97, v95
	v_max_f32_e32 v94, v96, v94
	v_max_f32_e32 v100, v104, v105
	v_min_f32_e32 v93, v101, v91
	v_max_f32_e32 v92, v101, v91
	v_min_f32_e32 v91, v99, v90
	v_max_f32_e32 v90, v99, v90
	v_min_f32_e32 v99, v98, v95
	v_min_f32_e32 v96, v94, v100
	v_max_f32_e32 v98, v98, v95
	v_max_f32_e32 v94, v94, v100
	s_ashr_i32 s7, s6, 31
	v_min_f32_e32 v97, v99, v96
	v_max_f32_e32 v96, v99, v96
	v_min_f32_e32 v95, v98, v94
	v_max_f32_e32 v94, v98, v94
	v_lshl_add_u64 v[98:99], s[6:7], 2, v[64:65]
	v_min_f32_e32 v89, v106, v88
	v_max_f32_e32 v88, v106, v88
	global_store_dwordx4 v[98:99], v[94:97], off
	global_store_dwordx4 v[98:99], v[90:93], off offset:16
	global_store_dwordx4 v[98:99], v[86:89], off offset:32
	global_store_dwordx4 v[98:99], v[82:85], off offset:48

; __global__ void __launch_bounds__(512) mega(Params p) {
;   extern __shared__ __attribute__((aligned(16))) char lds[];
	.amdhsa_kernel _Z4mega6Params
		.amdhsa_group_segment_fixed_size 0
		.amdhsa_private_segment_fixed_size 0
		.amdhsa_kernarg_size 472
		.amdhsa_user_sgpr_count 2
		.amdhsa_user_sgpr_dispatch_ptr 0
		.amdhsa_user_sgpr_queue_ptr 0
		.amdhsa_user_sgpr_kernarg_segment_ptr 1
		.amdhsa_user_sgpr_dispatch_id 0
		.amdhsa_user_sgpr_kernarg_preload_length 0
		.amdhsa_user_sgpr_kernarg_preload_offset 0
		.amdhsa_user_sgpr_private_segment_size 0
		.amdhsa_uses_dynamic_stack 0
		.amdhsa_enable_private_segment 0
		.amdhsa_system_sgpr_workgroup_id_x 1
		.amdhsa_system_sgpr_workgroup_id_y 0
		.amdhsa_system_sgpr_workgroup_id_z 0
		.amdhsa_system_sgpr_workgroup_info 0
		.amdhsa_system_vgpr_workitem_id 2
		.amdhsa_next_free_vgpr 256
		.amdhsa_next_free_sgpr 98
		.amdhsa_accum_offset 256
		.amdhsa_reserve_vcc 1
		.amdhsa_float_round_mode_32 0
		.amdhsa_float_round_mode_16_64 0
		.amdhsa_float_denorm_mode_32 3
		.amdhsa_float_denorm_mode_16_64 3
		.amdhsa_dx10_clamp 1
		.amdhsa_ieee_mode 1
		.amdhsa_fp16_overflow 0
		.amdhsa_tg_split 0
		.amdhsa_exception_fp_ieee_invalid_op 0
		.amdhsa_exception_fp_denorm_src 0
		.amdhsa_exception_fp_ieee_div_zero 0
		.amdhsa_exception_fp_ieee_overflow 0
		.amdhsa_exception_fp_ieee_underflow 0
		.amdhsa_exception_fp_ieee_inexact 0
		.amdhsa_exception_int_div_zero 0
	.end_amdhsa_kernel

; __global__ void __launch_bounds__(512) mega(Params p) {
;   extern __shared__ __attribute__((aligned(16))) char lds[];
amdhsa.kernels:
  - .agpr_count:     0
    .args:
      - .offset:         0
        .size:           216
        .value_kind:     by_value
      - .offset:         216
        .size:           4
        .value_kind:     hidden_block_count_x
      - .offset:         220
        .size:           4
        .value_kind:     hidden_block_count_y
      - .offset:         224
        .size:           4
        .value_kind:     hidden_block_count_z
      - .offset:         228
        .size:           2
        .value_kind:     hidden_group_size_x
      - .offset:         230
        .size:           2
        .value_kind:     hidden_group_size_y
      - .offset:         232
        .size:           2
        .value_kind:     hidden_group_size_z
      - .offset:         234
        .size:           2
        .value_kind:     hidden_remainder_x
      - .offset:         236
        .size:           2
        .value_kind:     hidden_remainder_y
      - .offset:         238
        .size:           2
        .value_kind:     hidden_remainder_z
      - .offset:         256
        .size:           8
        .value_kind:     hidden_global_offset_x
      - .offset:         264
        .size:           8
        .value_kind:     hidden_global_offset_y
      - .offset:         272
        .size:           8
        .value_kind:     hidden_global_offset_z
      - .offset:         280
        .size:           2
        .value_kind:     hidden_grid_dims
      - .offset:         304
        .size:           8
        .value_kind:     hidden_multigrid_sync_arg
      - .offset:         336
        .size:           4
        .value_kind:     hidden_dynamic_lds_size
    .group_segment_fixed_size: 0
    .kernarg_segment_align: 8
    .kernarg_segment_size: 472
    .language:       OpenCL C
    .language_version:
      - 2
      - 0
    .max_flat_workgroup_size: 512
    .name:           _Z4mega6Params
    .private_segment_fixed_size: 0
    .sgpr_count:     104
    .sgpr_spill_count: 60
    .symbol:         _Z4mega6Params.kd
    .uniform_work_group_size: 1
    .uses_dynamic_stack: false
    .vgpr_count:     256
    .vgpr_spill_count: 0
    .wavefront_size: 64
